# opt11
# speedup vs baseline: 1.0557x; 1.0022x over previous
; __device__ __forceinline__ float b2f(u16 b) { return __uint_as_float(((uint32_t)b) << 16); }
; __device__ __forceinline__ float sigmoidf_(float x) { return 1.0f / (1.0f + __expf(-x)); }
; __device__ __forceinline__ void gemm_phase(const Ctx& cx, const GemmArgs& g_, char* shm) {
;     ...
;               const uint2 gv = *(const uint2*)(g.gate + (size_t)tok * NP + n0);
;               float v0 = sigmoidf_(b2f((u16)(gv.x & 0xffff))) * a[0], v1 = sigmoidf_(b2f((u16)(gv.x >> 16))) * a[1];
;               float v2 = sigmoidf_(b2f((u16)(gv.y & 0xffff))) * a[2], v3 = sigmoidf_(b2f((u16)(gv.y >> 16))) * a[3];
;               uint2* mp = (uint2*)(g.outb + (size_t)tok * DM + n0);
;               if (g.epi != EPI_BR0) {
;                 const uint2 pv = *mp;
;                 v0 += b2f((u16)(pv.x & 0xffff)); v1 += b2f((u16)(pv.x >> 16));
;                 v2 += b2f((u16)(pv.y & 0xffff)); v3 += b2f((u16)(pv.y >> 16));
;               }
;               uint2 o; o.x = pack2(v0, v1); o.y = pack2(v2, v3);
;               *mp = o;
.Lmy_fast_br:
	v_or_b32_e32 v194, s4, v168
	v_add_u32_e32 v186, s2, v169
	v_add_u32_e32 v188, v186, v170
	v_ashrrev_i32_e32 v189, 31, v188
	v_mad_i64_i32 v[184:185], s[6:7], v194, s39, 0
	v_lshl_add_u64 v[184:185], v[184:185], 1, s[20:21]
	v_lshl_add_u64 v[184:185], v[188:189], 1, v[184:185]
	s_lshl_b32 s6, s39, 4
	s_sub_i32 s6, 64, s6
	v_and_b32_e32 v192, 8, v168
	v_cmp_ne_u32_e32 vcc, 0, v192
	v_mov_b32_e32 v193, s6
	s_nop 1
	v_cndmask_b32_e32 v192, 0, v193, vcc
	v_cndmask_b32_e64 v193, 0, -1, vcc
	v_lshl_add_u64 v[184:185], v[184:185], 0, v[192:193]
	s_lshl_b32 s6, s39, 4
	s_mov_b32 s7, 0
	s_lshl_b32 s8, s39, 5
	s_mov_b32 s9, 0
	s_lshl_b32 s10, s39, 8
	s_mov_b32 s11, 0
	v_add_u32_e32 v186, v186, v0
	v_ashrrev_i32_e32 v187, 31, v186
	v_add_u32_e32 v195, 0, v194
	v_mov_b64_e32 v[244:245], s[22:23]
	v_mad_i64_i32 v[244:245], s[4:5], v195, s76, v[244:245]
	v_lshl_add_u64 v[244:245], v[186:187], 1, v[244:245]
	global_load_dwordx2 v[196:197], v[244:245], off offset:0
	global_load_dwordx2 v[198:199], v[244:245], off offset:32
	global_load_dwordx2 v[200:201], v[244:245], off offset:64
	global_load_dwordx2 v[202:203], v[244:245], off offset:96
	s_and_b64 vcc, exec, s[44:45]
	s_cbranch_vccz .Lmy_br_nopv_ld_0
	v_mov_b32_e32 v192, v195
	v_ashrrev_i32_e32 v193, 31, v195
	v_lshlrev_b64 v[192:193], 12, v[192:193]
	v_lshl_add_u64 v[192:193], s[20:21], 0, v[192:193]
	v_lshl_add_u64 v[192:193], v[186:187], 1, v[192:193]
	global_load_dwordx2 v[204:205], v[192:193], off offset:0
	global_load_dwordx2 v[206:207], v[192:193], off offset:32
	global_load_dwordx2 v[208:209], v[192:193], off offset:64
	global_load_dwordx2 v[210:211], v[192:193], off offset:96
.Lmy_br_nopv_ld_0:
	v_mov_b32_e32 v188, v184
	v_mov_b32_e32 v189, v185
	v_lshl_add_u64 v[190:191], v[188:189], 0, s[6:7]
	v_add_u32_e32 v195, 0, v194
	v_mov_b64_e32 v[244:245], s[22:23]
	v_mad_i64_i32 v[244:245], s[4:5], v195, s76, v[244:245]
	v_lshl_add_u64 v[244:245], v[186:187], 1, v[244:245]
	global_load_dwordx2 v[212:213], v[244:245], off offset:256
	global_load_dwordx2 v[214:215], v[244:245], off offset:288
	global_load_dwordx2 v[216:217], v[244:245], off offset:320
	global_load_dwordx2 v[218:219], v[244:245], off offset:352
	s_and_b64 vcc, exec, s[44:45]
	s_cbranch_vccz .Lmy_br_nopv_ld_1
	v_mov_b32_e32 v192, v195
	v_ashrrev_i32_e32 v193, 31, v195
	v_lshlrev_b64 v[192:193], 12, v[192:193]
	v_lshl_add_u64 v[192:193], s[20:21], 0, v[192:193]
	v_lshl_add_u64 v[192:193], v[186:187], 1, v[192:193]
	global_load_dwordx2 v[220:221], v[192:193], off offset:256
	global_load_dwordx2 v[222:223], v[192:193], off offset:288
	global_load_dwordx2 v[224:225], v[192:193], off offset:320
	global_load_dwordx2 v[226:227], v[192:193], off offset:352
.Lmy_br_nopv_ld_1:
	s_and_b64 vcc, exec, s[44:45]
	s_cbranch_vccz .Lmy_br_w0_0
	s_waitcnt vmcnt(8)
	s_branch .Lmy_br_wj_0
.Lmy_br_w0_0:
	s_waitcnt vmcnt(4)
.Lmy_br_wj_0:
	v_lshlrev_b32_e32 v228, 16, v196
	v_mul_f32_e32 v228, 0xbfb8aa3b, v228
	v_exp_f32_e32 v229, v228
	s_nop 0
	v_add_f32_e32 v229, 1.0, v229
	s_nop 0
	v_div_scale_f32 v230, s[2:3], v229, v229, 1.0
	v_rcp_f32_e32 v231, v230
	s_nop 0
	v_fma_f32 v232, -v230, v231, 1.0
	v_fmac_f32_e32 v231, v232, v231
	v_div_scale_f32 v233, vcc, 1.0, v229, 1.0
	v_mul_f32_e32 v234, v233, v231
	v_fma_f32 v235, -v230, v234, v233
	v_fmac_f32_e32 v234, v235, v231
	v_fma_f32 v230, -v230, v234, v233
	v_div_fmas_f32 v230, v230, v231, v234
	v_div_fixup_f32 v230, v230, v229, 1.0
	v_mul_f32_e32 v128, v128, v230
	v_and_b32_e32 v228, 0xffff0000, v196
	v_mul_f32_e32 v228, 0xbfb8aa3b, v228
	v_exp_f32_e32 v229, v228
	s_nop 0
	v_add_f32_e32 v229, 1.0, v229
	s_nop 0
	v_div_scale_f32 v230, s[2:3], v229, v229, 1.0
	v_rcp_f32_e32 v231, v230
	s_nop 0
	v_fma_f32 v232, -v230, v231, 1.0
	v_fmac_f32_e32 v231, v232, v231
	v_div_scale_f32 v233, vcc, 1.0, v229, 1.0
	v_mul_f32_e32 v234, v233, v231
	v_fma_f32 v235, -v230, v234, v233
	v_fmac_f32_e32 v234, v235, v231
	v_fma_f32 v230, -v230, v234, v233
	v_div_fmas_f32 v230, v230, v231, v234
	v_div_fixup_f32 v230, v230, v229, 1.0
	v_mul_f32_e32 v129, v129, v230
	v_lshlrev_b32_e32 v228, 16, v197
	v_mul_f32_e32 v228, 0xbfb8aa3b, v228
	v_exp_f32_e32 v229, v228
	s_nop 0
	v_add_f32_e32 v229, 1.0, v229
	s_nop 0
	v_div_scale_f32 v230, s[2:3], v229, v229, 1.0
	v_rcp_f32_e32 v231, v230
	s_nop 0
	v_fma_f32 v232, -v230, v231, 1.0
	v_fmac_f32_e32 v231, v232, v231
	v_div_scale_f32 v233, vcc, 1.0, v229, 1.0
	v_mul_f32_e32 v234, v233, v231
	v_fma_f32 v235, -v230, v234, v233
	v_fmac_f32_e32 v234, v235, v231
	v_fma_f32 v230, -v230, v234, v233
	v_div_fmas_f32 v230, v230, v231, v234
	v_div_fixup_f32 v230, v230, v229, 1.0
	v_mul_f32_e32 v130, v130, v230
	v_and_b32_e32 v228, 0xffff0000, v197
	v_mul_f32_e32 v228, 0xbfb8aa3b, v228
	v_exp_f32_e32 v229, v228
	s_nop 0
	v_add_f32_e32 v229, 1.0, v229
	s_nop 0
	v_div_scale_f32 v230, s[2:3], v229, v229, 1.0
	v_rcp_f32_e32 v231, v230
	s_nop 0
	v_fma_f32 v232, -v230, v231, 1.0
	v_fmac_f32_e32 v231, v232, v231
	v_div_scale_f32 v233, vcc, 1.0, v229, 1.0
	v_mul_f32_e32 v234, v233, v231
	v_fma_f32 v235, -v230, v234, v233
	v_fmac_f32_e32 v234, v235, v231
	v_fma_f32 v230, -v230, v234, v233
	v_div_fmas_f32 v230, v230, v231, v234
	v_div_fixup_f32 v230, v230, v229, 1.0
	v_mul_f32_e32 v131, v131, v230
	v_lshlrev_b32_e32 v228, 16, v198
	v_mul_f32_e32 v228, 0xbfb8aa3b, v228
	v_exp_f32_e32 v229, v228
	s_nop 0
	v_add_f32_e32 v229, 1.0, v229
	s_nop 0
	v_div_scale_f32 v230, s[2:3], v229, v229, 1.0
	v_rcp_f32_e32 v231, v230
	s_nop 0
	v_fma_f32 v232, -v230, v231, 1.0
	v_fmac_f32_e32 v231, v232, v231
	v_div_scale_f32 v233, vcc, 1.0, v229, 1.0
	v_mul_f32_e32 v234, v233, v231
	v_fma_f32 v235, -v230, v234, v233
; __device__ __forceinline__ float b2f(u16 b) { return __uint_as_float(((uint32_t)b) << 16); }
; __device__ __forceinline__ float sigmoidf_(float x) { return 1.0f / (1.0f + __expf(-x)); }
; __device__ __forceinline__ void gemm_phase(const Ctx& cx, const GemmArgs& g_, char* shm) {
;     ...
;               const uint2 gv = *(const uint2*)(g.gate + (size_t)tok * NP + n0);
;               float v0 = sigmoidf_(b2f((u16)(gv.x & 0xffff))) * a[0], v1 = sigmoidf_(b2f((u16)(gv.x >> 16))) * a[1];
;               float v2 = sigmoidf_(b2f((u16)(gv.y & 0xffff))) * a[2], v3 = sigmoidf_(b2f((u16)(gv.y >> 16))) * a[3];
;               uint2* mp = (uint2*)(g.outb + (size_t)tok * DM + n0);
;               if (g.epi != EPI_BR0) {
;                 const uint2 pv = *mp;
;                 v0 += b2f((u16)(pv.x & 0xffff)); v1 += b2f((u16)(pv.x >> 16));
;                 v2 += b2f((u16)(pv.y & 0xffff)); v3 += b2f((u16)(pv.y >> 16));
;               }
;               uint2 o; o.x = pack2(v0, v1); o.y = pack2(v2, v3);
;               *mp = o;
	v_fmac_f32_e32 v234, v235, v231
	v_fma_f32 v230, -v230, v234, v233
	v_div_fmas_f32 v230, v230, v231, v234
	v_div_fixup_f32 v230, v230, v229, 1.0
	v_mul_f32_e32 v124, v124, v230
	v_and_b32_e32 v228, 0xffff0000, v198
	v_mul_f32_e32 v228, 0xbfb8aa3b, v228
	v_exp_f32_e32 v229, v228
	s_nop 0
	v_add_f32_e32 v229, 1.0, v229
	s_nop 0
	v_div_scale_f32 v230, s[2:3], v229, v229, 1.0
	v_rcp_f32_e32 v231, v230
	s_nop 0
	v_fma_f32 v232, -v230, v231, 1.0
	v_fmac_f32_e32 v231, v232, v231
	v_div_scale_f32 v233, vcc, 1.0, v229, 1.0
	v_mul_f32_e32 v234, v233, v231
	v_fma_f32 v235, -v230, v234, v233
	v_fmac_f32_e32 v234, v235, v231
	v_fma_f32 v230, -v230, v234, v233
	v_div_fmas_f32 v230, v230, v231, v234
	v_div_fixup_f32 v230, v230, v229, 1.0
	v_mul_f32_e32 v125, v125, v230
	v_lshlrev_b32_e32 v228, 16, v199
	v_mul_f32_e32 v228, 0xbfb8aa3b, v228
	v_exp_f32_e32 v229, v228
	s_nop 0
	v_add_f32_e32 v229, 1.0, v229
	s_nop 0
	v_div_scale_f32 v230, s[2:3], v229, v229, 1.0
	v_rcp_f32_e32 v231, v230
	s_nop 0
	v_fma_f32 v232, -v230, v231, 1.0
	v_fmac_f32_e32 v231, v232, v231
	v_div_scale_f32 v233, vcc, 1.0, v229, 1.0
	v_mul_f32_e32 v234, v233, v231
	v_fma_f32 v235, -v230, v234, v233
	v_fmac_f32_e32 v234, v235, v231
	v_fma_f32 v230, -v230, v234, v233
	v_div_fmas_f32 v230, v230, v231, v234
	v_div_fixup_f32 v230, v230, v229, 1.0
	v_mul_f32_e32 v126, v126, v230
	v_and_b32_e32 v228, 0xffff0000, v199
	v_mul_f32_e32 v228, 0xbfb8aa3b, v228
	v_exp_f32_e32 v229, v228
	s_nop 0
	v_add_f32_e32 v229, 1.0, v229
	s_nop 0
	v_div_scale_f32 v230, s[2:3], v229, v229, 1.0
	v_rcp_f32_e32 v231, v230
	s_nop 0
	v_fma_f32 v232, -v230, v231, 1.0
	v_fmac_f32_e32 v231, v232, v231
	v_div_scale_f32 v233, vcc, 1.0, v229, 1.0
	v_mul_f32_e32 v234, v233, v231
	v_fma_f32 v235, -v230, v234, v233
	v_fmac_f32_e32 v234, v235, v231
	v_fma_f32 v230, -v230, v234, v233
	v_div_fmas_f32 v230, v230, v231, v234
	v_div_fixup_f32 v230, v230, v229, 1.0
	v_mul_f32_e32 v127, v127, v230
	s_and_b64 vcc, exec, s[44:45]
	s_cbranch_vccz .Lmy_br_nopv_add_0_0
	v_lshlrev_b32_e32 v228, 16, v204
	v_add_f32_e32 v128, v128, v228
	v_and_b32_e32 v228, 0xffff0000, v204
	v_add_f32_e32 v129, v129, v228
	v_lshlrev_b32_e32 v228, 16, v205
	v_add_f32_e32 v130, v130, v228
	v_and_b32_e32 v228, 0xffff0000, v205
	v_add_f32_e32 v131, v131, v228
	v_lshlrev_b32_e32 v228, 16, v206
	v_add_f32_e32 v124, v124, v228
	v_and_b32_e32 v228, 0xffff0000, v206
	v_add_f32_e32 v125, v125, v228
	v_lshlrev_b32_e32 v228, 16, v207
	v_add_f32_e32 v126, v126, v228
	v_and_b32_e32 v228, 0xffff0000, v207
	v_add_f32_e32 v127, v127, v228
.Lmy_br_nopv_add_0_0:
	v_cvt_pk_bf16_f32 v236, v128, v129
	v_cvt_pk_bf16_f32 v237, v130, v131
	v_cvt_pk_bf16_f32 v238, v124, v125
	v_cvt_pk_bf16_f32 v239, v126, v127
	s_nop 1
	v_permlane16_swap_b32_e32 v236, v238
	v_permlane16_swap_b32_e32 v237, v239
	v_lshlrev_b32_e32 v228, 16, v200
	v_mul_f32_e32 v228, 0xbfb8aa3b, v228
	v_exp_f32_e32 v229, v228
	s_nop 0
	v_add_f32_e32 v229, 1.0, v229
	s_nop 0
	v_div_scale_f32 v230, s[2:3], v229, v229, 1.0
	v_rcp_f32_e32 v231, v230
	s_nop 0
	v_fma_f32 v232, -v230, v231, 1.0
	v_fmac_f32_e32 v231, v232, v231
	v_div_scale_f32 v233, vcc, 1.0, v229, 1.0
	v_mul_f32_e32 v234, v233, v231
	v_fma_f32 v235, -v230, v234, v233
	v_fmac_f32_e32 v234, v235, v231
	v_fma_f32 v230, -v230, v234, v233
	v_div_fmas_f32 v230, v230, v231, v234
	v_div_fixup_f32 v230, v230, v229, 1.0
	v_mul_f32_e32 v120, v120, v230
	v_and_b32_e32 v228, 0xffff0000, v200
	v_mul_f32_e32 v228, 0xbfb8aa3b, v228
	v_exp_f32_e32 v229, v228
	s_nop 0
	v_add_f32_e32 v229, 1.0, v229
	s_nop 0
	v_div_scale_f32 v230, s[2:3], v229, v229, 1.0
	v_rcp_f32_e32 v231, v230
	s_nop 0
	v_fma_f32 v232, -v230, v231, 1.0
	v_fmac_f32_e32 v231, v232, v231
	v_div_scale_f32 v233, vcc, 1.0, v229, 1.0
	v_mul_f32_e32 v234, v233, v231
	v_fma_f32 v235, -v230, v234, v233
	v_fmac_f32_e32 v234, v235, v231
	v_fma_f32 v230, -v230, v234, v233
	v_div_fmas_f32 v230, v230, v231, v234
	v_div_fixup_f32 v230, v230, v229, 1.0
	v_mul_f32_e32 v121, v121, v230
	v_lshlrev_b32_e32 v228, 16, v201
	v_mul_f32_e32 v228, 0xbfb8aa3b, v228
	v_exp_f32_e32 v229, v228
	s_nop 0
	v_add_f32_e32 v229, 1.0, v229
	s_nop 0
	v_div_scale_f32 v230, s[2:3], v229, v229, 1.0
	v_rcp_f32_e32 v231, v230
	s_nop 0
	v_fma_f32 v232, -v230, v231, 1.0
	v_fmac_f32_e32 v231, v232, v231
	v_div_scale_f32 v233, vcc, 1.0, v229, 1.0
	v_mul_f32_e32 v234, v233, v231
	v_fma_f32 v235, -v230, v234, v233
	v_fmac_f32_e32 v234, v235, v231
	v_fma_f32 v230, -v230, v234, v233
	v_div_fmas_f32 v230, v230, v231, v234
	v_div_fixup_f32 v230, v230, v229, 1.0
	v_mul_f32_e32 v122, v122, v230
	v_and_b32_e32 v228, 0xffff0000, v201
	v_mul_f32_e32 v228, 0xbfb8aa3b, v228
	v_exp_f32_e32 v229, v228
	s_nop 0
	v_add_f32_e32 v229, 1.0, v229
	s_nop 0
	v_div_scale_f32 v230, s[2:3], v229, v229, 1.0
	v_rcp_f32_e32 v231, v230
	s_nop 0
	v_fma_f32 v232, -v230, v231, 1.0
	v_fmac_f32_e32 v231, v232, v231
	v_div_scale_f32 v233, vcc, 1.0, v229, 1.0
	v_mul_f32_e32 v234, v233, v231
	v_fma_f32 v235, -v230, v234, v233
	v_fmac_f32_e32 v234, v235, v231
	v_fma_f32 v230, -v230, v234, v233
	v_div_fmas_f32 v230, v230, v231, v234
	v_div_fixup_f32 v230, v230, v229, 1.0
	v_mul_f32_e32 v123, v123, v230
	v_lshlrev_b32_e32 v228, 16, v202
	v_mul_f32_e32 v228, 0xbfb8aa3b, v228
	v_exp_f32_e32 v229, v228
	s_nop 0
	v_add_f32_e32 v229, 1.0, v229
	s_nop 0
	v_div_scale_f32 v230, s[2:3], v229, v229, 1.0
	v_rcp_f32_e32 v231, v230
	s_nop 0
	v_fma_f32 v232, -v230, v231, 1.0
	v_fmac_f32_e32 v231, v232, v231
	v_div_scale_f32 v233, vcc, 1.0, v229, 1.0
	v_mul_f32_e32 v234, v233, v231
	v_fma_f32 v235, -v230, v234, v233
	v_fmac_f32_e32 v234, v235, v231
	v_fma_f32 v230, -v230, v234, v233
	v_div_fmas_f32 v230, v230, v231, v234
; __device__ __forceinline__ float b2f(u16 b) { return __uint_as_float(((uint32_t)b) << 16); }
; __device__ __forceinline__ float sigmoidf_(float x) { return 1.0f / (1.0f + __expf(-x)); }
; __device__ __forceinline__ void gemm_phase(const Ctx& cx, const GemmArgs& g_, char* shm) {
;     ...
;               const uint2 gv = *(const uint2*)(g.gate + (size_t)tok * NP + n0);
;               float v0 = sigmoidf_(b2f((u16)(gv.x & 0xffff))) * a[0], v1 = sigmoidf_(b2f((u16)(gv.x >> 16))) * a[1];
;               float v2 = sigmoidf_(b2f((u16)(gv.y & 0xffff))) * a[2], v3 = sigmoidf_(b2f((u16)(gv.y >> 16))) * a[3];
;               uint2* mp = (uint2*)(g.outb + (size_t)tok * DM + n0);
;               if (g.epi != EPI_BR0) {
;                 const uint2 pv = *mp;
;                 v0 += b2f((u16)(pv.x & 0xffff)); v1 += b2f((u16)(pv.x >> 16));
;                 v2 += b2f((u16)(pv.y & 0xffff)); v3 += b2f((u16)(pv.y >> 16));
;               }
;               uint2 o; o.x = pack2(v0, v1); o.y = pack2(v2, v3);
;               *mp = o;
	v_div_fixup_f32 v230, v230, v229, 1.0
	v_mul_f32_e32 v116, v116, v230
	v_and_b32_e32 v228, 0xffff0000, v202
	v_mul_f32_e32 v228, 0xbfb8aa3b, v228
	v_exp_f32_e32 v229, v228
	s_nop 0
	v_add_f32_e32 v229, 1.0, v229
	s_nop 0
	v_div_scale_f32 v230, s[2:3], v229, v229, 1.0
	v_rcp_f32_e32 v231, v230
	s_nop 0
	v_fma_f32 v232, -v230, v231, 1.0
	v_fmac_f32_e32 v231, v232, v231
	v_div_scale_f32 v233, vcc, 1.0, v229, 1.0
	v_mul_f32_e32 v234, v233, v231
	v_fma_f32 v235, -v230, v234, v233
	v_fmac_f32_e32 v234, v235, v231
	v_fma_f32 v230, -v230, v234, v233
	v_div_fmas_f32 v230, v230, v231, v234
	v_div_fixup_f32 v230, v230, v229, 1.0
	v_mul_f32_e32 v117, v117, v230
	v_lshlrev_b32_e32 v228, 16, v203
	v_mul_f32_e32 v228, 0xbfb8aa3b, v228
	v_exp_f32_e32 v229, v228
	s_nop 0
	v_add_f32_e32 v229, 1.0, v229
	s_nop 0
	v_div_scale_f32 v230, s[2:3], v229, v229, 1.0
	v_rcp_f32_e32 v231, v230
	s_nop 0
	v_fma_f32 v232, -v230, v231, 1.0
	v_fmac_f32_e32 v231, v232, v231
	v_div_scale_f32 v233, vcc, 1.0, v229, 1.0
	v_mul_f32_e32 v234, v233, v231
	v_fma_f32 v235, -v230, v234, v233
	v_fmac_f32_e32 v234, v235, v231
	v_fma_f32 v230, -v230, v234, v233
	v_div_fmas_f32 v230, v230, v231, v234
	v_div_fixup_f32 v230, v230, v229, 1.0
	v_mul_f32_e32 v118, v118, v230
	v_and_b32_e32 v228, 0xffff0000, v203
	v_mul_f32_e32 v228, 0xbfb8aa3b, v228
	v_exp_f32_e32 v229, v228
	s_nop 0
	v_add_f32_e32 v229, 1.0, v229
	s_nop 0
	v_div_scale_f32 v230, s[2:3], v229, v229, 1.0
	v_rcp_f32_e32 v231, v230
	s_nop 0
	v_fma_f32 v232, -v230, v231, 1.0
	v_fmac_f32_e32 v231, v232, v231
	v_div_scale_f32 v233, vcc, 1.0, v229, 1.0
	v_mul_f32_e32 v234, v233, v231
	v_fma_f32 v235, -v230, v234, v233
	v_fmac_f32_e32 v234, v235, v231
	v_fma_f32 v230, -v230, v234, v233
	v_div_fmas_f32 v230, v230, v231, v234
	v_div_fixup_f32 v230, v230, v229, 1.0
	v_mul_f32_e32 v119, v119, v230
	s_and_b64 vcc, exec, s[44:45]
	s_cbranch_vccz .Lmy_br_nopv_add_0_1
	v_lshlrev_b32_e32 v228, 16, v208
	v_add_f32_e32 v120, v120, v228
	v_and_b32_e32 v228, 0xffff0000, v208
	v_add_f32_e32 v121, v121, v228
	v_lshlrev_b32_e32 v228, 16, v209
	v_add_f32_e32 v122, v122, v228
	v_and_b32_e32 v228, 0xffff0000, v209
	v_add_f32_e32 v123, v123, v228
	v_lshlrev_b32_e32 v228, 16, v210
	v_add_f32_e32 v116, v116, v228
	v_and_b32_e32 v228, 0xffff0000, v210
	v_add_f32_e32 v117, v117, v228
	v_lshlrev_b32_e32 v228, 16, v211
	v_add_f32_e32 v118, v118, v228
	v_and_b32_e32 v228, 0xffff0000, v211
	v_add_f32_e32 v119, v119, v228
.Lmy_br_nopv_add_0_1:
	v_cvt_pk_bf16_f32 v240, v120, v121
	v_cvt_pk_bf16_f32 v241, v122, v123
	v_cvt_pk_bf16_f32 v242, v116, v117
	v_cvt_pk_bf16_f32 v243, v118, v119
	s_nop 1
	v_permlane16_swap_b32_e32 v240, v242
	v_permlane16_swap_b32_e32 v241, v243
	v_mov_b32_e32 v244, v240
	v_mov_b32_e32 v245, v241
	v_mov_b32_e32 v246, v242
	v_mov_b32_e32 v247, v243
	v_mov_b32_dpp v240, v236 row_ror:8 row_mask:0xf bank_mask:0x3
	v_mov_b32_dpp v241, v237 row_ror:8 row_mask:0xf bank_mask:0x3
	v_mov_b32_dpp v242, v238 row_ror:8 row_mask:0xf bank_mask:0x3
	v_mov_b32_dpp v243, v239 row_ror:8 row_mask:0xf bank_mask:0x3
	v_mov_b32_dpp v236, v244 row_ror:8 row_mask:0xf bank_mask:0xc
	v_mov_b32_dpp v237, v245 row_ror:8 row_mask:0xf bank_mask:0xc
	v_mov_b32_dpp v238, v246 row_ror:8 row_mask:0xf bank_mask:0xc
	v_mov_b32_dpp v239, v247 row_ror:8 row_mask:0xf bank_mask:0xc
	global_store_dwordx4 v[188:189], v[236:239], off offset:32
	global_store_dwordx4 v[190:191], v[240:243], off offset:32
	s_nop 1
	v_add_u32_e32 v195, 16, v194
	v_mov_b64_e32 v[244:245], s[22:23]
	v_mad_i64_i32 v[244:245], s[4:5], v195, s76, v[244:245]
	v_lshl_add_u64 v[244:245], v[186:187], 1, v[244:245]
	global_load_dwordx2 v[196:197], v[244:245], off offset:0
	global_load_dwordx2 v[198:199], v[244:245], off offset:32
	global_load_dwordx2 v[200:201], v[244:245], off offset:64
	global_load_dwordx2 v[202:203], v[244:245], off offset:96
	s_and_b64 vcc, exec, s[44:45]
	s_cbranch_vccz .Lmy_br_nopv_ld_2
	v_mov_b32_e32 v192, v195
	v_ashrrev_i32_e32 v193, 31, v195
	v_lshlrev_b64 v[192:193], 12, v[192:193]
	v_lshl_add_u64 v[192:193], s[20:21], 0, v[192:193]
	v_lshl_add_u64 v[192:193], v[186:187], 1, v[192:193]
	global_load_dwordx2 v[204:205], v[192:193], off offset:0
	global_load_dwordx2 v[206:207], v[192:193], off offset:32
	global_load_dwordx2 v[208:209], v[192:193], off offset:64
	global_load_dwordx2 v[210:211], v[192:193], off offset:96
.Lmy_br_nopv_ld_2:
	s_and_b64 vcc, exec, s[44:45]
	s_cbranch_vccz .Lmy_br_w0_1
	s_waitcnt vmcnt(10)
	s_branch .Lmy_br_wj_1
.Lmy_br_w0_1:
	s_waitcnt vmcnt(6)
; __device__ __forceinline__ float b2f(u16 b) { return __uint_as_float(((uint32_t)b) << 16); }
; __device__ __forceinline__ float sigmoidf_(float x) { return 1.0f / (1.0f + __expf(-x)); }
; __device__ __forceinline__ void gemm_phase(const Ctx& cx, const GemmArgs& g_, char* shm) {
;     ...
;               const uint2 gv = *(const uint2*)(g.gate + (size_t)tok * NP + n0);
;               float v0 = sigmoidf_(b2f((u16)(gv.x & 0xffff))) * a[0], v1 = sigmoidf_(b2f((u16)(gv.x >> 16))) * a[1];
;               float v2 = sigmoidf_(b2f((u16)(gv.y & 0xffff))) * a[2], v3 = sigmoidf_(b2f((u16)(gv.y >> 16))) * a[3];
;               uint2* mp = (uint2*)(g.outb + (size_t)tok * DM + n0);
;               if (g.epi != EPI_BR0) {
;                 const uint2 pv = *mp;
;                 v0 += b2f((u16)(pv.x & 0xffff)); v1 += b2f((u16)(pv.x >> 16));
;                 v2 += b2f((u16)(pv.y & 0xffff)); v3 += b2f((u16)(pv.y >> 16));
;               }
;               uint2 o; o.x = pack2(v0, v1); o.y = pack2(v2, v3);
;               *mp = o;
.Lmy_br_wj_1:
	v_lshlrev_b32_e32 v228, 16, v212
	v_mul_f32_e32 v228, 0xbfb8aa3b, v228
	v_exp_f32_e32 v229, v228
	s_nop 0
	v_add_f32_e32 v229, 1.0, v229
	s_nop 0
	v_div_scale_f32 v230, s[2:3], v229, v229, 1.0
	v_rcp_f32_e32 v231, v230
	s_nop 0
	v_fma_f32 v232, -v230, v231, 1.0
	v_fmac_f32_e32 v231, v232, v231
	v_div_scale_f32 v233, vcc, 1.0, v229, 1.0
	v_mul_f32_e32 v234, v233, v231
	v_fma_f32 v235, -v230, v234, v233
	v_fmac_f32_e32 v234, v235, v231
	v_fma_f32 v230, -v230, v234, v233
	v_div_fmas_f32 v230, v230, v231, v234
	v_div_fixup_f32 v230, v230, v229, 1.0
	v_mul_f32_e32 v112, v112, v230
	v_and_b32_e32 v228, 0xffff0000, v212
	v_mul_f32_e32 v228, 0xbfb8aa3b, v228
	v_exp_f32_e32 v229, v228
	s_nop 0
	v_add_f32_e32 v229, 1.0, v229
	s_nop 0
	v_div_scale_f32 v230, s[2:3], v229, v229, 1.0
	v_rcp_f32_e32 v231, v230
	s_nop 0
	v_fma_f32 v232, -v230, v231, 1.0
	v_fmac_f32_e32 v231, v232, v231
	v_div_scale_f32 v233, vcc, 1.0, v229, 1.0
	v_mul_f32_e32 v234, v233, v231
	v_fma_f32 v235, -v230, v234, v233
	v_fmac_f32_e32 v234, v235, v231
	v_fma_f32 v230, -v230, v234, v233
	v_div_fmas_f32 v230, v230, v231, v234
	v_div_fixup_f32 v230, v230, v229, 1.0
	v_mul_f32_e32 v113, v113, v230
	v_lshlrev_b32_e32 v228, 16, v213
	v_mul_f32_e32 v228, 0xbfb8aa3b, v228
	v_exp_f32_e32 v229, v228
	s_nop 0
	v_add_f32_e32 v229, 1.0, v229
	s_nop 0
	v_div_scale_f32 v230, s[2:3], v229, v229, 1.0
	v_rcp_f32_e32 v231, v230
	s_nop 0
	v_fma_f32 v232, -v230, v231, 1.0
	v_fmac_f32_e32 v231, v232, v231
	v_div_scale_f32 v233, vcc, 1.0, v229, 1.0
	v_mul_f32_e32 v234, v233, v231
	v_fma_f32 v235, -v230, v234, v233
	v_fmac_f32_e32 v234, v235, v231
	v_fma_f32 v230, -v230, v234, v233
	v_div_fmas_f32 v230, v230, v231, v234
	v_div_fixup_f32 v230, v230, v229, 1.0
	v_mul_f32_e32 v114, v114, v230
	v_and_b32_e32 v228, 0xffff0000, v213
	v_mul_f32_e32 v228, 0xbfb8aa3b, v228
	v_exp_f32_e32 v229, v228
	s_nop 0
	v_add_f32_e32 v229, 1.0, v229
	s_nop 0
	v_div_scale_f32 v230, s[2:3], v229, v229, 1.0
	v_rcp_f32_e32 v231, v230
	s_nop 0
	v_fma_f32 v232, -v230, v231, 1.0
	v_fmac_f32_e32 v231, v232, v231
	v_div_scale_f32 v233, vcc, 1.0, v229, 1.0
	v_mul_f32_e32 v234, v233, v231
	v_fma_f32 v235, -v230, v234, v233
	v_fmac_f32_e32 v234, v235, v231
	v_fma_f32 v230, -v230, v234, v233
	v_div_fmas_f32 v230, v230, v231, v234
	v_div_fixup_f32 v230, v230, v229, 1.0
	v_mul_f32_e32 v115, v115, v230
	v_lshlrev_b32_e32 v228, 16, v214
	v_mul_f32_e32 v228, 0xbfb8aa3b, v228
	v_exp_f32_e32 v229, v228
	s_nop 0
	v_add_f32_e32 v229, 1.0, v229
	s_nop 0
	v_div_scale_f32 v230, s[2:3], v229, v229, 1.0
	v_rcp_f32_e32 v231, v230
	s_nop 0
	v_fma_f32 v232, -v230, v231, 1.0
	v_fmac_f32_e32 v231, v232, v231
	v_div_scale_f32 v233, vcc, 1.0, v229, 1.0
	v_mul_f32_e32 v234, v233, v231
	v_fma_f32 v235, -v230, v234, v233
	v_fmac_f32_e32 v234, v235, v231
	v_fma_f32 v230, -v230, v234, v233
	v_div_fmas_f32 v230, v230, v231, v234
	v_div_fixup_f32 v230, v230, v229, 1.0
	v_mul_f32_e32 v108, v108, v230
	v_and_b32_e32 v228, 0xffff0000, v214
	v_mul_f32_e32 v228, 0xbfb8aa3b, v228
	v_exp_f32_e32 v229, v228
	s_nop 0
	v_add_f32_e32 v229, 1.0, v229
	s_nop 0
	v_div_scale_f32 v230, s[2:3], v229, v229, 1.0
	v_rcp_f32_e32 v231, v230
	s_nop 0
	v_fma_f32 v232, -v230, v231, 1.0
	v_fmac_f32_e32 v231, v232, v231
	v_div_scale_f32 v233, vcc, 1.0, v229, 1.0
	v_mul_f32_e32 v234, v233, v231
	v_fma_f32 v235, -v230, v234, v233
	v_fmac_f32_e32 v234, v235, v231
	v_fma_f32 v230, -v230, v234, v233
	v_div_fmas_f32 v230, v230, v231, v234
	v_div_fixup_f32 v230, v230, v229, 1.0
	v_mul_f32_e32 v109, v109, v230
	v_lshlrev_b32_e32 v228, 16, v215
	v_mul_f32_e32 v228, 0xbfb8aa3b, v228
	v_exp_f32_e32 v229, v228
	s_nop 0
	v_add_f32_e32 v229, 1.0, v229
	s_nop 0
	v_div_scale_f32 v230, s[2:3], v229, v229, 1.0
	v_rcp_f32_e32 v231, v230
	s_nop 0
	v_fma_f32 v232, -v230, v231, 1.0
	v_fmac_f32_e32 v231, v232, v231
	v_div_scale_f32 v233, vcc, 1.0, v229, 1.0
	v_mul_f32_e32 v234, v233, v231
	v_fma_f32 v235, -v230, v234, v233
	v_fmac_f32_e32 v234, v235, v231
	v_fma_f32 v230, -v230, v234, v233
	v_div_fmas_f32 v230, v230, v231, v234
	v_div_fixup_f32 v230, v230, v229, 1.0
	v_mul_f32_e32 v110, v110, v230
	v_and_b32_e32 v228, 0xffff0000, v215
	v_mul_f32_e32 v228, 0xbfb8aa3b, v228
	v_exp_f32_e32 v229, v228
	s_nop 0
	v_add_f32_e32 v229, 1.0, v229
	s_nop 0
	v_div_scale_f32 v230, s[2:3], v229, v229, 1.0
	v_rcp_f32_e32 v231, v230
	s_nop 0
	v_fma_f32 v232, -v230, v231, 1.0
	v_fmac_f32_e32 v231, v232, v231
	v_div_scale_f32 v233, vcc, 1.0, v229, 1.0
	v_mul_f32_e32 v234, v233, v231
	v_fma_f32 v235, -v230, v234, v233
	v_fmac_f32_e32 v234, v235, v231
	v_fma_f32 v230, -v230, v234, v233
	v_div_fmas_f32 v230, v230, v231, v234
	v_div_fixup_f32 v230, v230, v229, 1.0
	v_mul_f32_e32 v111, v111, v230
	s_and_b64 vcc, exec, s[44:45]
	s_cbranch_vccz .Lmy_br_nopv_add_1_0
	v_lshlrev_b32_e32 v228, 16, v220
	v_add_f32_e32 v112, v112, v228
	v_and_b32_e32 v228, 0xffff0000, v220
	v_add_f32_e32 v113, v113, v228
	v_lshlrev_b32_e32 v228, 16, v221
	v_add_f32_e32 v114, v114, v228
	v_and_b32_e32 v228, 0xffff0000, v221
	v_add_f32_e32 v115, v115, v228
	v_lshlrev_b32_e32 v228, 16, v222
	v_add_f32_e32 v108, v108, v228
	v_and_b32_e32 v228, 0xffff0000, v222
	v_add_f32_e32 v109, v109, v228
	v_lshlrev_b32_e32 v228, 16, v223
	v_add_f32_e32 v110, v110, v228
	v_and_b32_e32 v228, 0xffff0000, v223
	v_add_f32_e32 v111, v111, v228
; __device__ __forceinline__ float b2f(u16 b) { return __uint_as_float(((uint32_t)b) << 16); }
; __device__ __forceinline__ float sigmoidf_(float x) { return 1.0f / (1.0f + __expf(-x)); }
; __device__ __forceinline__ void gemm_phase(const Ctx& cx, const GemmArgs& g_, char* shm) {
;     ...
;               const uint2 gv = *(const uint2*)(g.gate + (size_t)tok * NP + n0);
;               float v0 = sigmoidf_(b2f((u16)(gv.x & 0xffff))) * a[0], v1 = sigmoidf_(b2f((u16)(gv.x >> 16))) * a[1];
;               float v2 = sigmoidf_(b2f((u16)(gv.y & 0xffff))) * a[2], v3 = sigmoidf_(b2f((u16)(gv.y >> 16))) * a[3];
;               uint2* mp = (uint2*)(g.outb + (size_t)tok * DM + n0);
;               if (g.epi != EPI_BR0) {
;                 const uint2 pv = *mp;
;                 v0 += b2f((u16)(pv.x & 0xffff)); v1 += b2f((u16)(pv.x >> 16));
;                 v2 += b2f((u16)(pv.y & 0xffff)); v3 += b2f((u16)(pv.y >> 16));
;               }
;               uint2 o; o.x = pack2(v0, v1); o.y = pack2(v2, v3);
;               *mp = o;
.Lmy_br_nopv_add_1_0:
	v_cvt_pk_bf16_f32 v236, v112, v113
	v_cvt_pk_bf16_f32 v237, v114, v115
	v_cvt_pk_bf16_f32 v238, v108, v109
	v_cvt_pk_bf16_f32 v239, v110, v111
	s_nop 1
	v_permlane16_swap_b32_e32 v236, v238
	v_permlane16_swap_b32_e32 v237, v239
	v_lshlrev_b32_e32 v228, 16, v216
	v_mul_f32_e32 v228, 0xbfb8aa3b, v228
	v_exp_f32_e32 v229, v228
	s_nop 0
	v_add_f32_e32 v229, 1.0, v229
	s_nop 0
	v_div_scale_f32 v230, s[2:3], v229, v229, 1.0
	v_rcp_f32_e32 v231, v230
	s_nop 0
	v_fma_f32 v232, -v230, v231, 1.0
	v_fmac_f32_e32 v231, v232, v231
	v_div_scale_f32 v233, vcc, 1.0, v229, 1.0
	v_mul_f32_e32 v234, v233, v231
	v_fma_f32 v235, -v230, v234, v233
	v_fmac_f32_e32 v234, v235, v231
	v_fma_f32 v230, -v230, v234, v233
	v_div_fmas_f32 v230, v230, v231, v234
	v_div_fixup_f32 v230, v230, v229, 1.0
	v_mul_f32_e32 v104, v104, v230
	v_and_b32_e32 v228, 0xffff0000, v216
	v_mul_f32_e32 v228, 0xbfb8aa3b, v228
	v_exp_f32_e32 v229, v228
	s_nop 0
	v_add_f32_e32 v229, 1.0, v229
	s_nop 0
	v_div_scale_f32 v230, s[2:3], v229, v229, 1.0
	v_rcp_f32_e32 v231, v230
	s_nop 0
	v_fma_f32 v232, -v230, v231, 1.0
	v_fmac_f32_e32 v231, v232, v231
	v_div_scale_f32 v233, vcc, 1.0, v229, 1.0
	v_mul_f32_e32 v234, v233, v231
	v_fma_f32 v235, -v230, v234, v233
	v_fmac_f32_e32 v234, v235, v231
	v_fma_f32 v230, -v230, v234, v233
	v_div_fmas_f32 v230, v230, v231, v234
	v_div_fixup_f32 v230, v230, v229, 1.0
	v_mul_f32_e32 v105, v105, v230
	v_lshlrev_b32_e32 v228, 16, v217
	v_mul_f32_e32 v228, 0xbfb8aa3b, v228
	v_exp_f32_e32 v229, v228
	s_nop 0
	v_add_f32_e32 v229, 1.0, v229
	s_nop 0
	v_div_scale_f32 v230, s[2:3], v229, v229, 1.0
	v_rcp_f32_e32 v231, v230
	s_nop 0
	v_fma_f32 v232, -v230, v231, 1.0
	v_fmac_f32_e32 v231, v232, v231
	v_div_scale_f32 v233, vcc, 1.0, v229, 1.0
	v_mul_f32_e32 v234, v233, v231
	v_fma_f32 v235, -v230, v234, v233
	v_fmac_f32_e32 v234, v235, v231
	v_fma_f32 v230, -v230, v234, v233
	v_div_fmas_f32 v230, v230, v231, v234
	v_div_fixup_f32 v230, v230, v229, 1.0
	v_mul_f32_e32 v106, v106, v230
	v_and_b32_e32 v228, 0xffff0000, v217
	v_mul_f32_e32 v228, 0xbfb8aa3b, v228
	v_exp_f32_e32 v229, v228
	s_nop 0
	v_add_f32_e32 v229, 1.0, v229
	s_nop 0
	v_div_scale_f32 v230, s[2:3], v229, v229, 1.0
	v_rcp_f32_e32 v231, v230
	s_nop 0
	v_fma_f32 v232, -v230, v231, 1.0
	v_fmac_f32_e32 v231, v232, v231
	v_div_scale_f32 v233, vcc, 1.0, v229, 1.0
	v_mul_f32_e32 v234, v233, v231
	v_fma_f32 v235, -v230, v234, v233
	v_fmac_f32_e32 v234, v235, v231
	v_fma_f32 v230, -v230, v234, v233
	v_div_fmas_f32 v230, v230, v231, v234
	v_div_fixup_f32 v230, v230, v229, 1.0
	v_mul_f32_e32 v107, v107, v230
	v_lshlrev_b32_e32 v228, 16, v218
	v_mul_f32_e32 v228, 0xbfb8aa3b, v228
	v_exp_f32_e32 v229, v228
	s_nop 0
	v_add_f32_e32 v229, 1.0, v229
	s_nop 0
	v_div_scale_f32 v230, s[2:3], v229, v229, 1.0
	v_rcp_f32_e32 v231, v230
	s_nop 0
	v_fma_f32 v232, -v230, v231, 1.0
	v_fmac_f32_e32 v231, v232, v231
	v_div_scale_f32 v233, vcc, 1.0, v229, 1.0
	v_mul_f32_e32 v234, v233, v231
	v_fma_f32 v235, -v230, v234, v233
	v_fmac_f32_e32 v234, v235, v231
	v_fma_f32 v230, -v230, v234, v233
	v_div_fmas_f32 v230, v230, v231, v234
	v_div_fixup_f32 v230, v230, v229, 1.0
	v_mul_f32_e32 v100, v100, v230
	v_and_b32_e32 v228, 0xffff0000, v218
	v_mul_f32_e32 v228, 0xbfb8aa3b, v228
	v_exp_f32_e32 v229, v228
	s_nop 0
	v_add_f32_e32 v229, 1.0, v229
	s_nop 0
	v_div_scale_f32 v230, s[2:3], v229, v229, 1.0
	v_rcp_f32_e32 v231, v230
	s_nop 0
	v_fma_f32 v232, -v230, v231, 1.0
	v_fmac_f32_e32 v231, v232, v231
	v_div_scale_f32 v233, vcc, 1.0, v229, 1.0
	v_mul_f32_e32 v234, v233, v231
	v_fma_f32 v235, -v230, v234, v233
	v_fmac_f32_e32 v234, v235, v231
	v_fma_f32 v230, -v230, v234, v233
	v_div_fmas_f32 v230, v230, v231, v234
	v_div_fixup_f32 v230, v230, v229, 1.0
	v_mul_f32_e32 v101, v101, v230
	v_lshlrev_b32_e32 v228, 16, v219
	v_mul_f32_e32 v228, 0xbfb8aa3b, v228
	v_exp_f32_e32 v229, v228
	s_nop 0
	v_add_f32_e32 v229, 1.0, v229
	s_nop 0
	v_div_scale_f32 v230, s[2:3], v229, v229, 1.0
	v_rcp_f32_e32 v231, v230
	s_nop 0
	v_fma_f32 v232, -v230, v231, 1.0
	v_fmac_f32_e32 v231, v232, v231
	v_div_scale_f32 v233, vcc, 1.0, v229, 1.0
	v_mul_f32_e32 v234, v233, v231
	v_fma_f32 v235, -v230, v234, v233
	v_fmac_f32_e32 v234, v235, v231
	v_fma_f32 v230, -v230, v234, v233
	v_div_fmas_f32 v230, v230, v231, v234
	v_div_fixup_f32 v230, v230, v229, 1.0
	v_mul_f32_e32 v102, v102, v230
	v_and_b32_e32 v228, 0xffff0000, v219
	v_mul_f32_e32 v228, 0xbfb8aa3b, v228
	v_exp_f32_e32 v229, v228
	s_nop 0
	v_add_f32_e32 v229, 1.0, v229
	s_nop 0
	v_div_scale_f32 v230, s[2:3], v229, v229, 1.0
	v_rcp_f32_e32 v231, v230
	s_nop 0
	v_fma_f32 v232, -v230, v231, 1.0
	v_fmac_f32_e32 v231, v232, v231
	v_div_scale_f32 v233, vcc, 1.0, v229, 1.0
	v_mul_f32_e32 v234, v233, v231
	v_fma_f32 v235, -v230, v234, v233
	v_fmac_f32_e32 v234, v235, v231
	v_fma_f32 v230, -v230, v234, v233
	v_div_fmas_f32 v230, v230, v231, v234
	v_div_fixup_f32 v230, v230, v229, 1.0
	v_mul_f32_e32 v103, v103, v230
	s_and_b64 vcc, exec, s[44:45]
	s_cbranch_vccz .Lmy_br_nopv_add_1_1
	v_lshlrev_b32_e32 v228, 16, v224
	v_add_f32_e32 v104, v104, v228
	v_and_b32_e32 v228, 0xffff0000, v224
	v_add_f32_e32 v105, v105, v228
	v_lshlrev_b32_e32 v228, 16, v225
	v_add_f32_e32 v106, v106, v228
	v_and_b32_e32 v228, 0xffff0000, v225
	v_add_f32_e32 v107, v107, v228
	v_lshlrev_b32_e32 v228, 16, v226
	v_add_f32_e32 v100, v100, v228
	v_and_b32_e32 v228, 0xffff0000, v226
	v_add_f32_e32 v101, v101, v228
	v_lshlrev_b32_e32 v228, 16, v227
	v_add_f32_e32 v102, v102, v228
	v_and_b32_e32 v228, 0xffff0000, v227
	v_add_f32_e32 v103, v103, v228
; __device__ __forceinline__ float b2f(u16 b) { return __uint_as_float(((uint32_t)b) << 16); }
; __device__ __forceinline__ float sigmoidf_(float x) { return 1.0f / (1.0f + __expf(-x)); }
; __device__ __forceinline__ void gemm_phase(const Ctx& cx, const GemmArgs& g_, char* shm) {
;     ...
;               const uint2 gv = *(const uint2*)(g.gate + (size_t)tok * NP + n0);
;               float v0 = sigmoidf_(b2f((u16)(gv.x & 0xffff))) * a[0], v1 = sigmoidf_(b2f((u16)(gv.x >> 16))) * a[1];
;               float v2 = sigmoidf_(b2f((u16)(gv.y & 0xffff))) * a[2], v3 = sigmoidf_(b2f((u16)(gv.y >> 16))) * a[3];
;               uint2* mp = (uint2*)(g.outb + (size_t)tok * DM + n0);
;               if (g.epi != EPI_BR0) {
;                 const uint2 pv = *mp;
;                 v0 += b2f((u16)(pv.x & 0xffff)); v1 += b2f((u16)(pv.x >> 16));
;                 v2 += b2f((u16)(pv.y & 0xffff)); v3 += b2f((u16)(pv.y >> 16));
;               }
;               uint2 o; o.x = pack2(v0, v1); o.y = pack2(v2, v3);
;               *mp = o;
.Lmy_br_nopv_add_1_1:
	v_cvt_pk_bf16_f32 v240, v104, v105
	v_cvt_pk_bf16_f32 v241, v106, v107
	v_cvt_pk_bf16_f32 v242, v100, v101
	v_cvt_pk_bf16_f32 v243, v102, v103
	s_nop 1
	v_permlane16_swap_b32_e32 v240, v242
	v_permlane16_swap_b32_e32 v241, v243
	v_mov_b32_e32 v244, v240
	v_mov_b32_e32 v245, v241
	v_mov_b32_e32 v246, v242
	v_mov_b32_e32 v247, v243
	v_mov_b32_dpp v240, v236 row_ror:8 row_mask:0xf bank_mask:0x3
	v_mov_b32_dpp v241, v237 row_ror:8 row_mask:0xf bank_mask:0x3
	v_mov_b32_dpp v242, v238 row_ror:8 row_mask:0xf bank_mask:0x3
	v_mov_b32_dpp v243, v239 row_ror:8 row_mask:0xf bank_mask:0x3
	v_mov_b32_dpp v236, v244 row_ror:8 row_mask:0xf bank_mask:0xc
	v_mov_b32_dpp v237, v245 row_ror:8 row_mask:0xf bank_mask:0xc
	v_mov_b32_dpp v238, v246 row_ror:8 row_mask:0xf bank_mask:0xc
	v_mov_b32_dpp v239, v247 row_ror:8 row_mask:0xf bank_mask:0xc
	global_store_dwordx4 v[188:189], v[236:239], off offset:288
	global_store_dwordx4 v[190:191], v[240:243], off offset:288
	s_nop 1
	v_lshl_add_u64 v[188:189], v[184:185], 0, s[8:9]
	v_lshl_add_u64 v[190:191], v[188:189], 0, s[6:7]
	v_add_u32_e32 v195, 16, v194
	v_mov_b64_e32 v[244:245], s[22:23]
	v_mad_i64_i32 v[244:245], s[4:5], v195, s76, v[244:245]
	v_lshl_add_u64 v[244:245], v[186:187], 1, v[244:245]
	global_load_dwordx2 v[212:213], v[244:245], off offset:256
	global_load_dwordx2 v[214:215], v[244:245], off offset:288
	global_load_dwordx2 v[216:217], v[244:245], off offset:320
	global_load_dwordx2 v[218:219], v[244:245], off offset:352
	s_and_b64 vcc, exec, s[44:45]
	s_cbranch_vccz .Lmy_br_nopv_ld_3
	v_mov_b32_e32 v192, v195
	v_ashrrev_i32_e32 v193, 31, v195
	v_lshlrev_b64 v[192:193], 12, v[192:193]
	v_lshl_add_u64 v[192:193], s[20:21], 0, v[192:193]
	v_lshl_add_u64 v[192:193], v[186:187], 1, v[192:193]
	global_load_dwordx2 v[220:221], v[192:193], off offset:256
	global_load_dwordx2 v[222:223], v[192:193], off offset:288
	global_load_dwordx2 v[224:225], v[192:193], off offset:320
	global_load_dwordx2 v[226:227], v[192:193], off offset:352

; __device__ __forceinline__ float b2f(u16 b) { return __uint_as_float(((uint32_t)b) << 16); }
; __device__ __forceinline__ float sigmoidf_(float x) { return 1.0f / (1.0f + __expf(-x)); }
; __device__ __forceinline__ void gemm_phase(const Ctx& cx, const GemmArgs& g_, char* shm) {
;     ...
;               const uint2 gv = *(const uint2*)(g.gate + (size_t)tok * NP + n0);
;               float v0 = sigmoidf_(b2f((u16)(gv.x & 0xffff))) * a[0], v1 = sigmoidf_(b2f((u16)(gv.x >> 16))) * a[1];
;               float v2 = sigmoidf_(b2f((u16)(gv.y & 0xffff))) * a[2], v3 = sigmoidf_(b2f((u16)(gv.y >> 16))) * a[3];
;               uint2* mp = (uint2*)(g.outb + (size_t)tok * DM + n0);
;               if (g.epi != EPI_BR0) {
;                 const uint2 pv = *mp;
;                 v0 += b2f((u16)(pv.x & 0xffff)); v1 += b2f((u16)(pv.x >> 16));
;                 v2 += b2f((u16)(pv.y & 0xffff)); v3 += b2f((u16)(pv.y >> 16));
;               }
;               uint2 o; o.x = pack2(v0, v1); o.y = pack2(v2, v3);
;               *mp = o;
.Lmy_br_wj_2:
	v_lshlrev_b32_e32 v228, 16, v196
	v_mul_f32_e32 v228, 0xbfb8aa3b, v228
	v_exp_f32_e32 v229, v228
	s_nop 0
	v_add_f32_e32 v229, 1.0, v229
	s_nop 0
	v_div_scale_f32 v230, s[2:3], v229, v229, 1.0
	v_rcp_f32_e32 v231, v230
	s_nop 0
	v_fma_f32 v232, -v230, v231, 1.0
	v_fmac_f32_e32 v231, v232, v231
	v_div_scale_f32 v233, vcc, 1.0, v229, 1.0
	v_mul_f32_e32 v234, v233, v231
	v_fma_f32 v235, -v230, v234, v233
	v_fmac_f32_e32 v234, v235, v231
	v_fma_f32 v230, -v230, v234, v233
	v_div_fmas_f32 v230, v230, v231, v234
	v_div_fixup_f32 v230, v230, v229, 1.0
	v_mul_f32_e32 v96, v96, v230
	v_and_b32_e32 v228, 0xffff0000, v196
	v_mul_f32_e32 v228, 0xbfb8aa3b, v228
	v_exp_f32_e32 v229, v228
	s_nop 0
	v_add_f32_e32 v229, 1.0, v229
	s_nop 0
	v_div_scale_f32 v230, s[2:3], v229, v229, 1.0
	v_rcp_f32_e32 v231, v230
	s_nop 0
	v_fma_f32 v232, -v230, v231, 1.0
	v_fmac_f32_e32 v231, v232, v231
	v_div_scale_f32 v233, vcc, 1.0, v229, 1.0
	v_mul_f32_e32 v234, v233, v231
	v_fma_f32 v235, -v230, v234, v233
	v_fmac_f32_e32 v234, v235, v231
	v_fma_f32 v230, -v230, v234, v233
	v_div_fmas_f32 v230, v230, v231, v234
	v_div_fixup_f32 v230, v230, v229, 1.0
	v_mul_f32_e32 v97, v97, v230
	v_lshlrev_b32_e32 v228, 16, v197
	v_mul_f32_e32 v228, 0xbfb8aa3b, v228
	v_exp_f32_e32 v229, v228
	s_nop 0
	v_add_f32_e32 v229, 1.0, v229
	s_nop 0
	v_div_scale_f32 v230, s[2:3], v229, v229, 1.0
	v_rcp_f32_e32 v231, v230
	s_nop 0
	v_fma_f32 v232, -v230, v231, 1.0
	v_fmac_f32_e32 v231, v232, v231
	v_div_scale_f32 v233, vcc, 1.0, v229, 1.0
	v_mul_f32_e32 v234, v233, v231
	v_fma_f32 v235, -v230, v234, v233
	v_fmac_f32_e32 v234, v235, v231
	v_fma_f32 v230, -v230, v234, v233
	v_div_fmas_f32 v230, v230, v231, v234
	v_div_fixup_f32 v230, v230, v229, 1.0
	v_mul_f32_e32 v98, v98, v230
	v_and_b32_e32 v228, 0xffff0000, v197
	v_mul_f32_e32 v228, 0xbfb8aa3b, v228
	v_exp_f32_e32 v229, v228
	s_nop 0
	v_add_f32_e32 v229, 1.0, v229
	s_nop 0
	v_div_scale_f32 v230, s[2:3], v229, v229, 1.0
	v_rcp_f32_e32 v231, v230
	s_nop 0
	v_fma_f32 v232, -v230, v231, 1.0
	v_fmac_f32_e32 v231, v232, v231
	v_div_scale_f32 v233, vcc, 1.0, v229, 1.0
	v_mul_f32_e32 v234, v233, v231
	v_fma_f32 v235, -v230, v234, v233
	v_fmac_f32_e32 v234, v235, v231
	v_fma_f32 v230, -v230, v234, v233
	v_div_fmas_f32 v230, v230, v231, v234
	v_div_fixup_f32 v230, v230, v229, 1.0
	v_mul_f32_e32 v99, v99, v230
	v_lshlrev_b32_e32 v228, 16, v198
	v_mul_f32_e32 v228, 0xbfb8aa3b, v228
	v_exp_f32_e32 v229, v228
	s_nop 0
	v_add_f32_e32 v229, 1.0, v229
	s_nop 0
	v_div_scale_f32 v230, s[2:3], v229, v229, 1.0
	v_rcp_f32_e32 v231, v230
	s_nop 0
	v_fma_f32 v232, -v230, v231, 1.0
	v_fmac_f32_e32 v231, v232, v231
	v_div_scale_f32 v233, vcc, 1.0, v229, 1.0
	v_mul_f32_e32 v234, v233, v231
	v_fma_f32 v235, -v230, v234, v233
	v_fmac_f32_e32 v234, v235, v231
	v_fma_f32 v230, -v230, v234, v233
	v_div_fmas_f32 v230, v230, v231, v234
	v_div_fixup_f32 v230, v230, v229, 1.0
	v_mul_f32_e32 v92, v92, v230
	v_and_b32_e32 v228, 0xffff0000, v198
	v_mul_f32_e32 v228, 0xbfb8aa3b, v228
	v_exp_f32_e32 v229, v228
	s_nop 0
	v_add_f32_e32 v229, 1.0, v229
	s_nop 0
	v_div_scale_f32 v230, s[2:3], v229, v229, 1.0
	v_rcp_f32_e32 v231, v230
	s_nop 0
	v_fma_f32 v232, -v230, v231, 1.0
	v_fmac_f32_e32 v231, v232, v231
	v_div_scale_f32 v233, vcc, 1.0, v229, 1.0
	v_mul_f32_e32 v234, v233, v231
	v_fma_f32 v235, -v230, v234, v233
	v_fmac_f32_e32 v234, v235, v231
	v_fma_f32 v230, -v230, v234, v233
	v_div_fmas_f32 v230, v230, v231, v234
	v_div_fixup_f32 v230, v230, v229, 1.0
	v_mul_f32_e32 v93, v93, v230
	v_lshlrev_b32_e32 v228, 16, v199
	v_mul_f32_e32 v228, 0xbfb8aa3b, v228
	v_exp_f32_e32 v229, v228
	s_nop 0
	v_add_f32_e32 v229, 1.0, v229
	s_nop 0
	v_div_scale_f32 v230, s[2:3], v229, v229, 1.0
	v_rcp_f32_e32 v231, v230
	s_nop 0
	v_fma_f32 v232, -v230, v231, 1.0
	v_fmac_f32_e32 v231, v232, v231
	v_div_scale_f32 v233, vcc, 1.0, v229, 1.0
	v_mul_f32_e32 v234, v233, v231
	v_fma_f32 v235, -v230, v234, v233
	v_fmac_f32_e32 v234, v235, v231
	v_fma_f32 v230, -v230, v234, v233
	v_div_fmas_f32 v230, v230, v231, v234
	v_div_fixup_f32 v230, v230, v229, 1.0
	v_mul_f32_e32 v94, v94, v230
	v_and_b32_e32 v228, 0xffff0000, v199
	v_mul_f32_e32 v228, 0xbfb8aa3b, v228
	v_exp_f32_e32 v229, v228
	s_nop 0
	v_add_f32_e32 v229, 1.0, v229
	s_nop 0
	v_div_scale_f32 v230, s[2:3], v229, v229, 1.0
	v_rcp_f32_e32 v231, v230
	s_nop 0
	v_fma_f32 v232, -v230, v231, 1.0
	v_fmac_f32_e32 v231, v232, v231
	v_div_scale_f32 v233, vcc, 1.0, v229, 1.0
	v_mul_f32_e32 v234, v233, v231
	v_fma_f32 v235, -v230, v234, v233
	v_fmac_f32_e32 v234, v235, v231
	v_fma_f32 v230, -v230, v234, v233
	v_div_fmas_f32 v230, v230, v231, v234
	v_div_fixup_f32 v230, v230, v229, 1.0
	v_mul_f32_e32 v95, v95, v230
	s_and_b64 vcc, exec, s[44:45]
	s_cbranch_vccz .Lmy_br_nopv_add_2_0
	v_lshlrev_b32_e32 v228, 16, v204
	v_add_f32_e32 v96, v96, v228
	v_and_b32_e32 v228, 0xffff0000, v204
	v_add_f32_e32 v97, v97, v228
	v_lshlrev_b32_e32 v228, 16, v205
	v_add_f32_e32 v98, v98, v228
	v_and_b32_e32 v228, 0xffff0000, v205
	v_add_f32_e32 v99, v99, v228
	v_lshlrev_b32_e32 v228, 16, v206
	v_add_f32_e32 v92, v92, v228
	v_and_b32_e32 v228, 0xffff0000, v206
	v_add_f32_e32 v93, v93, v228
	v_lshlrev_b32_e32 v228, 16, v207
	v_add_f32_e32 v94, v94, v228
	v_and_b32_e32 v228, 0xffff0000, v207
	v_add_f32_e32 v95, v95, v228
; __device__ __forceinline__ float b2f(u16 b) { return __uint_as_float(((uint32_t)b) << 16); }
; __device__ __forceinline__ float sigmoidf_(float x) { return 1.0f / (1.0f + __expf(-x)); }
; __device__ __forceinline__ void gemm_phase(const Ctx& cx, const GemmArgs& g_, char* shm) {
;     ...
;               const uint2 gv = *(const uint2*)(g.gate + (size_t)tok * NP + n0);
;               float v0 = sigmoidf_(b2f((u16)(gv.x & 0xffff))) * a[0], v1 = sigmoidf_(b2f((u16)(gv.x >> 16))) * a[1];
;               float v2 = sigmoidf_(b2f((u16)(gv.y & 0xffff))) * a[2], v3 = sigmoidf_(b2f((u16)(gv.y >> 16))) * a[3];
;               uint2* mp = (uint2*)(g.outb + (size_t)tok * DM + n0);
;               if (g.epi != EPI_BR0) {
;                 const uint2 pv = *mp;
;                 v0 += b2f((u16)(pv.x & 0xffff)); v1 += b2f((u16)(pv.x >> 16));
;                 v2 += b2f((u16)(pv.y & 0xffff)); v3 += b2f((u16)(pv.y >> 16));
;               }
;               uint2 o; o.x = pack2(v0, v1); o.y = pack2(v2, v3);
;               *mp = o;
.Lmy_br_nopv_add_2_0:
	v_cvt_pk_bf16_f32 v236, v96, v97
	v_cvt_pk_bf16_f32 v237, v98, v99
	v_cvt_pk_bf16_f32 v238, v92, v93
	v_cvt_pk_bf16_f32 v239, v94, v95
	s_nop 1
	v_permlane16_swap_b32_e32 v236, v238
	v_permlane16_swap_b32_e32 v237, v239
	v_lshlrev_b32_e32 v228, 16, v200
	v_mul_f32_e32 v228, 0xbfb8aa3b, v228
	v_exp_f32_e32 v229, v228
	s_nop 0
	v_add_f32_e32 v229, 1.0, v229
	s_nop 0
	v_div_scale_f32 v230, s[2:3], v229, v229, 1.0
	v_rcp_f32_e32 v231, v230
	s_nop 0
	v_fma_f32 v232, -v230, v231, 1.0
	v_fmac_f32_e32 v231, v232, v231
	v_div_scale_f32 v233, vcc, 1.0, v229, 1.0
	v_mul_f32_e32 v234, v233, v231
	v_fma_f32 v235, -v230, v234, v233
	v_fmac_f32_e32 v234, v235, v231
	v_fma_f32 v230, -v230, v234, v233
	v_div_fmas_f32 v230, v230, v231, v234
	v_div_fixup_f32 v230, v230, v229, 1.0
	v_mul_f32_e32 v88, v88, v230
	v_and_b32_e32 v228, 0xffff0000, v200
	v_mul_f32_e32 v228, 0xbfb8aa3b, v228
	v_exp_f32_e32 v229, v228
	s_nop 0
	v_add_f32_e32 v229, 1.0, v229
	s_nop 0
	v_div_scale_f32 v230, s[2:3], v229, v229, 1.0
	v_rcp_f32_e32 v231, v230
	s_nop 0
	v_fma_f32 v232, -v230, v231, 1.0
	v_fmac_f32_e32 v231, v232, v231
	v_div_scale_f32 v233, vcc, 1.0, v229, 1.0
	v_mul_f32_e32 v234, v233, v231
	v_fma_f32 v235, -v230, v234, v233
	v_fmac_f32_e32 v234, v235, v231
	v_fma_f32 v230, -v230, v234, v233
	v_div_fmas_f32 v230, v230, v231, v234
	v_div_fixup_f32 v230, v230, v229, 1.0
	v_mul_f32_e32 v89, v89, v230
	v_lshlrev_b32_e32 v228, 16, v201
	v_mul_f32_e32 v228, 0xbfb8aa3b, v228
	v_exp_f32_e32 v229, v228
	s_nop 0
	v_add_f32_e32 v229, 1.0, v229
	s_nop 0
	v_div_scale_f32 v230, s[2:3], v229, v229, 1.0
	v_rcp_f32_e32 v231, v230
	s_nop 0
	v_fma_f32 v232, -v230, v231, 1.0
	v_fmac_f32_e32 v231, v232, v231
	v_div_scale_f32 v233, vcc, 1.0, v229, 1.0
	v_mul_f32_e32 v234, v233, v231
	v_fma_f32 v235, -v230, v234, v233
	v_fmac_f32_e32 v234, v235, v231
	v_fma_f32 v230, -v230, v234, v233
	v_div_fmas_f32 v230, v230, v231, v234
	v_div_fixup_f32 v230, v230, v229, 1.0
	v_mul_f32_e32 v90, v90, v230
	v_and_b32_e32 v228, 0xffff0000, v201
	v_mul_f32_e32 v228, 0xbfb8aa3b, v228
	v_exp_f32_e32 v229, v228
	s_nop 0
	v_add_f32_e32 v229, 1.0, v229
	s_nop 0
	v_div_scale_f32 v230, s[2:3], v229, v229, 1.0
	v_rcp_f32_e32 v231, v230
	s_nop 0
	v_fma_f32 v232, -v230, v231, 1.0
	v_fmac_f32_e32 v231, v232, v231
	v_div_scale_f32 v233, vcc, 1.0, v229, 1.0
	v_mul_f32_e32 v234, v233, v231
	v_fma_f32 v235, -v230, v234, v233
	v_fmac_f32_e32 v234, v235, v231
	v_fma_f32 v230, -v230, v234, v233
	v_div_fmas_f32 v230, v230, v231, v234
	v_div_fixup_f32 v230, v230, v229, 1.0
	v_mul_f32_e32 v91, v91, v230
	v_lshlrev_b32_e32 v228, 16, v202
	v_mul_f32_e32 v228, 0xbfb8aa3b, v228
	v_exp_f32_e32 v229, v228
	s_nop 0
	v_add_f32_e32 v229, 1.0, v229
	s_nop 0
	v_div_scale_f32 v230, s[2:3], v229, v229, 1.0
	v_rcp_f32_e32 v231, v230
	s_nop 0
	v_fma_f32 v232, -v230, v231, 1.0
	v_fmac_f32_e32 v231, v232, v231
	v_div_scale_f32 v233, vcc, 1.0, v229, 1.0
	v_mul_f32_e32 v234, v233, v231
	v_fma_f32 v235, -v230, v234, v233
	v_fmac_f32_e32 v234, v235, v231
	v_fma_f32 v230, -v230, v234, v233
	v_div_fmas_f32 v230, v230, v231, v234
	v_div_fixup_f32 v230, v230, v229, 1.0
	v_mul_f32_e32 v84, v84, v230
	v_and_b32_e32 v228, 0xffff0000, v202
	v_mul_f32_e32 v228, 0xbfb8aa3b, v228
	v_exp_f32_e32 v229, v228
	s_nop 0
	v_add_f32_e32 v229, 1.0, v229
	s_nop 0
	v_div_scale_f32 v230, s[2:3], v229, v229, 1.0
	v_rcp_f32_e32 v231, v230
	s_nop 0
	v_fma_f32 v232, -v230, v231, 1.0
	v_fmac_f32_e32 v231, v232, v231
	v_div_scale_f32 v233, vcc, 1.0, v229, 1.0
	v_mul_f32_e32 v234, v233, v231
	v_fma_f32 v235, -v230, v234, v233
	v_fmac_f32_e32 v234, v235, v231
	v_fma_f32 v230, -v230, v234, v233
	v_div_fmas_f32 v230, v230, v231, v234
	v_div_fixup_f32 v230, v230, v229, 1.0
	v_mul_f32_e32 v85, v85, v230
	v_lshlrev_b32_e32 v228, 16, v203
	v_mul_f32_e32 v228, 0xbfb8aa3b, v228
	v_exp_f32_e32 v229, v228
	s_nop 0
	v_add_f32_e32 v229, 1.0, v229
	s_nop 0
	v_div_scale_f32 v230, s[2:3], v229, v229, 1.0
	v_rcp_f32_e32 v231, v230
	s_nop 0
	v_fma_f32 v232, -v230, v231, 1.0
	v_fmac_f32_e32 v231, v232, v231
	v_div_scale_f32 v233, vcc, 1.0, v229, 1.0
	v_mul_f32_e32 v234, v233, v231
	v_fma_f32 v235, -v230, v234, v233
	v_fmac_f32_e32 v234, v235, v231
	v_fma_f32 v230, -v230, v234, v233
	v_div_fmas_f32 v230, v230, v231, v234
	v_div_fixup_f32 v230, v230, v229, 1.0
	v_mul_f32_e32 v86, v86, v230
	v_and_b32_e32 v228, 0xffff0000, v203
	v_mul_f32_e32 v228, 0xbfb8aa3b, v228
	v_exp_f32_e32 v229, v228
	s_nop 0
	v_add_f32_e32 v229, 1.0, v229
	s_nop 0
	v_div_scale_f32 v230, s[2:3], v229, v229, 1.0
	v_rcp_f32_e32 v231, v230
	s_nop 0
	v_fma_f32 v232, -v230, v231, 1.0
	v_fmac_f32_e32 v231, v232, v231
	v_div_scale_f32 v233, vcc, 1.0, v229, 1.0
	v_mul_f32_e32 v234, v233, v231
	v_fma_f32 v235, -v230, v234, v233
	v_fmac_f32_e32 v234, v235, v231
	v_fma_f32 v230, -v230, v234, v233
	v_div_fmas_f32 v230, v230, v231, v234
	v_div_fixup_f32 v230, v230, v229, 1.0
	v_mul_f32_e32 v87, v87, v230
	s_and_b64 vcc, exec, s[44:45]
	s_cbranch_vccz .Lmy_br_nopv_add_2_1
	v_lshlrev_b32_e32 v228, 16, v208
	v_add_f32_e32 v88, v88, v228
	v_and_b32_e32 v228, 0xffff0000, v208
	v_add_f32_e32 v89, v89, v228
	v_lshlrev_b32_e32 v228, 16, v209
	v_add_f32_e32 v90, v90, v228
	v_and_b32_e32 v228, 0xffff0000, v209
	v_add_f32_e32 v91, v91, v228
	v_lshlrev_b32_e32 v228, 16, v210
	v_add_f32_e32 v84, v84, v228
	v_and_b32_e32 v228, 0xffff0000, v210
	v_add_f32_e32 v85, v85, v228
	v_lshlrev_b32_e32 v228, 16, v211
	v_add_f32_e32 v86, v86, v228
	v_and_b32_e32 v228, 0xffff0000, v211
	v_add_f32_e32 v87, v87, v228
; __device__ __forceinline__ float b2f(u16 b) { return __uint_as_float(((uint32_t)b) << 16); }
; __device__ __forceinline__ float sigmoidf_(float x) { return 1.0f / (1.0f + __expf(-x)); }
; __device__ __forceinline__ void gemm_phase(const Ctx& cx, const GemmArgs& g_, char* shm) {
;     ...
;               const uint2 gv = *(const uint2*)(g.gate + (size_t)tok * NP + n0);
;               float v0 = sigmoidf_(b2f((u16)(gv.x & 0xffff))) * a[0], v1 = sigmoidf_(b2f((u16)(gv.x >> 16))) * a[1];
;               float v2 = sigmoidf_(b2f((u16)(gv.y & 0xffff))) * a[2], v3 = sigmoidf_(b2f((u16)(gv.y >> 16))) * a[3];
;               uint2* mp = (uint2*)(g.outb + (size_t)tok * DM + n0);
;               if (g.epi != EPI_BR0) {
;                 const uint2 pv = *mp;
;                 v0 += b2f((u16)(pv.x & 0xffff)); v1 += b2f((u16)(pv.x >> 16));
;                 v2 += b2f((u16)(pv.y & 0xffff)); v3 += b2f((u16)(pv.y >> 16));
;               }
;               uint2 o; o.x = pack2(v0, v1); o.y = pack2(v2, v3);
;               *mp = o;
.Lmy_br_nopv_add_2_1:
	v_cvt_pk_bf16_f32 v240, v88, v89
	v_cvt_pk_bf16_f32 v241, v90, v91
	v_cvt_pk_bf16_f32 v242, v84, v85
	v_cvt_pk_bf16_f32 v243, v86, v87
	s_nop 1
	v_permlane16_swap_b32_e32 v240, v242
	v_permlane16_swap_b32_e32 v241, v243
	v_mov_b32_e32 v244, v240
	v_mov_b32_e32 v245, v241
	v_mov_b32_e32 v246, v242
	v_mov_b32_e32 v247, v243
	v_mov_b32_dpp v240, v236 row_ror:8 row_mask:0xf bank_mask:0x3
	v_mov_b32_dpp v241, v237 row_ror:8 row_mask:0xf bank_mask:0x3
	v_mov_b32_dpp v242, v238 row_ror:8 row_mask:0xf bank_mask:0x3
	v_mov_b32_dpp v243, v239 row_ror:8 row_mask:0xf bank_mask:0x3
	v_mov_b32_dpp v236, v244 row_ror:8 row_mask:0xf bank_mask:0xc
	v_mov_b32_dpp v237, v245 row_ror:8 row_mask:0xf bank_mask:0xc
	v_mov_b32_dpp v238, v246 row_ror:8 row_mask:0xf bank_mask:0xc
	v_mov_b32_dpp v239, v247 row_ror:8 row_mask:0xf bank_mask:0xc
	global_store_dwordx4 v[188:189], v[236:239], off offset:32
	global_store_dwordx4 v[190:191], v[240:243], off offset:32
	s_nop 1
	v_add_u32_e32 v195, 128, v194
	v_mov_b64_e32 v[244:245], s[22:23]
	v_mad_i64_i32 v[244:245], s[4:5], v195, s76, v[244:245]
	v_lshl_add_u64 v[244:245], v[186:187], 1, v[244:245]
	global_load_dwordx2 v[196:197], v[244:245], off offset:0
	global_load_dwordx2 v[198:199], v[244:245], off offset:32
	global_load_dwordx2 v[200:201], v[244:245], off offset:64
	global_load_dwordx2 v[202:203], v[244:245], off offset:96
	s_and_b64 vcc, exec, s[44:45]
	s_cbranch_vccz .Lmy_br_nopv_ld_4
	v_mov_b32_e32 v192, v195
	v_ashrrev_i32_e32 v193, 31, v195
	v_lshlrev_b64 v[192:193], 12, v[192:193]
	v_lshl_add_u64 v[192:193], s[20:21], 0, v[192:193]
	v_lshl_add_u64 v[192:193], v[186:187], 1, v[192:193]
	global_load_dwordx2 v[204:205], v[192:193], off offset:0
	global_load_dwordx2 v[206:207], v[192:193], off offset:32
	global_load_dwordx2 v[208:209], v[192:193], off offset:64
	global_load_dwordx2 v[210:211], v[192:193], off offset:96

; __device__ __forceinline__ float b2f(u16 b) { return __uint_as_float(((uint32_t)b) << 16); }
; __device__ __forceinline__ float sigmoidf_(float x) { return 1.0f / (1.0f + __expf(-x)); }
; __device__ __forceinline__ void gemm_phase(const Ctx& cx, const GemmArgs& g_, char* shm) {
;     ...
;               const uint2 gv = *(const uint2*)(g.gate + (size_t)tok * NP + n0);
;               float v0 = sigmoidf_(b2f((u16)(gv.x & 0xffff))) * a[0], v1 = sigmoidf_(b2f((u16)(gv.x >> 16))) * a[1];
;               float v2 = sigmoidf_(b2f((u16)(gv.y & 0xffff))) * a[2], v3 = sigmoidf_(b2f((u16)(gv.y >> 16))) * a[3];
;               uint2* mp = (uint2*)(g.outb + (size_t)tok * DM + n0);
;               if (g.epi != EPI_BR0) {
;                 const uint2 pv = *mp;
;                 v0 += b2f((u16)(pv.x & 0xffff)); v1 += b2f((u16)(pv.x >> 16));
;                 v2 += b2f((u16)(pv.y & 0xffff)); v3 += b2f((u16)(pv.y >> 16));
;               }
;               uint2 o; o.x = pack2(v0, v1); o.y = pack2(v2, v3);
;               *mp = o;
.Lmy_br_wj_3:
	v_lshlrev_b32_e32 v228, 16, v212
	v_mul_f32_e32 v228, 0xbfb8aa3b, v228
	v_exp_f32_e32 v229, v228
	s_nop 0
	v_add_f32_e32 v229, 1.0, v229
	s_nop 0
	v_div_scale_f32 v230, s[2:3], v229, v229, 1.0
	v_rcp_f32_e32 v231, v230
	s_nop 0
	v_fma_f32 v232, -v230, v231, 1.0
	v_fmac_f32_e32 v231, v232, v231
	v_div_scale_f32 v233, vcc, 1.0, v229, 1.0
	v_mul_f32_e32 v234, v233, v231
	v_fma_f32 v235, -v230, v234, v233
	v_fmac_f32_e32 v234, v235, v231
	v_fma_f32 v230, -v230, v234, v233
	v_div_fmas_f32 v230, v230, v231, v234
	v_div_fixup_f32 v230, v230, v229, 1.0
	v_mul_f32_e32 v80, v80, v230
	v_and_b32_e32 v228, 0xffff0000, v212
	v_mul_f32_e32 v228, 0xbfb8aa3b, v228
	v_exp_f32_e32 v229, v228
	s_nop 0
	v_add_f32_e32 v229, 1.0, v229
	s_nop 0
	v_div_scale_f32 v230, s[2:3], v229, v229, 1.0
	v_rcp_f32_e32 v231, v230
	s_nop 0
	v_fma_f32 v232, -v230, v231, 1.0
	v_fmac_f32_e32 v231, v232, v231
	v_div_scale_f32 v233, vcc, 1.0, v229, 1.0
	v_mul_f32_e32 v234, v233, v231
	v_fma_f32 v235, -v230, v234, v233
	v_fmac_f32_e32 v234, v235, v231
	v_fma_f32 v230, -v230, v234, v233
	v_div_fmas_f32 v230, v230, v231, v234
	v_div_fixup_f32 v230, v230, v229, 1.0
	v_mul_f32_e32 v81, v81, v230
	v_lshlrev_b32_e32 v228, 16, v213
	v_mul_f32_e32 v228, 0xbfb8aa3b, v228
	v_exp_f32_e32 v229, v228
	s_nop 0
	v_add_f32_e32 v229, 1.0, v229
	s_nop 0
	v_div_scale_f32 v230, s[2:3], v229, v229, 1.0
	v_rcp_f32_e32 v231, v230
	s_nop 0
	v_fma_f32 v232, -v230, v231, 1.0
	v_fmac_f32_e32 v231, v232, v231
	v_div_scale_f32 v233, vcc, 1.0, v229, 1.0
	v_mul_f32_e32 v234, v233, v231
	v_fma_f32 v235, -v230, v234, v233
	v_fmac_f32_e32 v234, v235, v231
	v_fma_f32 v230, -v230, v234, v233
	v_div_fmas_f32 v230, v230, v231, v234
	v_div_fixup_f32 v230, v230, v229, 1.0
	v_mul_f32_e32 v82, v82, v230
	v_and_b32_e32 v228, 0xffff0000, v213
	v_mul_f32_e32 v228, 0xbfb8aa3b, v228
	v_exp_f32_e32 v229, v228
	s_nop 0
	v_add_f32_e32 v229, 1.0, v229
	s_nop 0
	v_div_scale_f32 v230, s[2:3], v229, v229, 1.0
	v_rcp_f32_e32 v231, v230
	s_nop 0
	v_fma_f32 v232, -v230, v231, 1.0
	v_fmac_f32_e32 v231, v232, v231
	v_div_scale_f32 v233, vcc, 1.0, v229, 1.0
	v_mul_f32_e32 v234, v233, v231
	v_fma_f32 v235, -v230, v234, v233
	v_fmac_f32_e32 v234, v235, v231
	v_fma_f32 v230, -v230, v234, v233
	v_div_fmas_f32 v230, v230, v231, v234
	v_div_fixup_f32 v230, v230, v229, 1.0
	v_mul_f32_e32 v83, v83, v230
	v_lshlrev_b32_e32 v228, 16, v214
	v_mul_f32_e32 v228, 0xbfb8aa3b, v228
	v_exp_f32_e32 v229, v228
	s_nop 0
	v_add_f32_e32 v229, 1.0, v229
	s_nop 0
	v_div_scale_f32 v230, s[2:3], v229, v229, 1.0
	v_rcp_f32_e32 v231, v230
	s_nop 0
	v_fma_f32 v232, -v230, v231, 1.0
	v_fmac_f32_e32 v231, v232, v231
	v_div_scale_f32 v233, vcc, 1.0, v229, 1.0
	v_mul_f32_e32 v234, v233, v231
	v_fma_f32 v235, -v230, v234, v233
	v_fmac_f32_e32 v234, v235, v231
	v_fma_f32 v230, -v230, v234, v233
	v_div_fmas_f32 v230, v230, v231, v234
	v_div_fixup_f32 v230, v230, v229, 1.0
	v_mul_f32_e32 v76, v76, v230
	v_and_b32_e32 v228, 0xffff0000, v214
	v_mul_f32_e32 v228, 0xbfb8aa3b, v228
	v_exp_f32_e32 v229, v228
	s_nop 0
	v_add_f32_e32 v229, 1.0, v229
	s_nop 0
	v_div_scale_f32 v230, s[2:3], v229, v229, 1.0
	v_rcp_f32_e32 v231, v230
	s_nop 0
	v_fma_f32 v232, -v230, v231, 1.0
	v_fmac_f32_e32 v231, v232, v231
	v_div_scale_f32 v233, vcc, 1.0, v229, 1.0
	v_mul_f32_e32 v234, v233, v231
	v_fma_f32 v235, -v230, v234, v233
	v_fmac_f32_e32 v234, v235, v231
	v_fma_f32 v230, -v230, v234, v233
	v_div_fmas_f32 v230, v230, v231, v234
	v_div_fixup_f32 v230, v230, v229, 1.0
	v_mul_f32_e32 v77, v77, v230
	v_lshlrev_b32_e32 v228, 16, v215
	v_mul_f32_e32 v228, 0xbfb8aa3b, v228
	v_exp_f32_e32 v229, v228
	s_nop 0
	v_add_f32_e32 v229, 1.0, v229
	s_nop 0
	v_div_scale_f32 v230, s[2:3], v229, v229, 1.0
	v_rcp_f32_e32 v231, v230
	s_nop 0
	v_fma_f32 v232, -v230, v231, 1.0
	v_fmac_f32_e32 v231, v232, v231
	v_div_scale_f32 v233, vcc, 1.0, v229, 1.0
	v_mul_f32_e32 v234, v233, v231
	v_fma_f32 v235, -v230, v234, v233
	v_fmac_f32_e32 v234, v235, v231
	v_fma_f32 v230, -v230, v234, v233
	v_div_fmas_f32 v230, v230, v231, v234
	v_div_fixup_f32 v230, v230, v229, 1.0
	v_mul_f32_e32 v78, v78, v230
	v_and_b32_e32 v228, 0xffff0000, v215
	v_mul_f32_e32 v228, 0xbfb8aa3b, v228
	v_exp_f32_e32 v229, v228
	s_nop 0
	v_add_f32_e32 v229, 1.0, v229
	s_nop 0
	v_div_scale_f32 v230, s[2:3], v229, v229, 1.0
	v_rcp_f32_e32 v231, v230
	s_nop 0
	v_fma_f32 v232, -v230, v231, 1.0
	v_fmac_f32_e32 v231, v232, v231
	v_div_scale_f32 v233, vcc, 1.0, v229, 1.0
	v_mul_f32_e32 v234, v233, v231
	v_fma_f32 v235, -v230, v234, v233
	v_fmac_f32_e32 v234, v235, v231
	v_fma_f32 v230, -v230, v234, v233
	v_div_fmas_f32 v230, v230, v231, v234
	v_div_fixup_f32 v230, v230, v229, 1.0
	v_mul_f32_e32 v79, v79, v230
	s_and_b64 vcc, exec, s[44:45]
	s_cbranch_vccz .Lmy_br_nopv_add_3_0
	v_lshlrev_b32_e32 v228, 16, v220
	v_add_f32_e32 v80, v80, v228
	v_and_b32_e32 v228, 0xffff0000, v220
	v_add_f32_e32 v81, v81, v228
	v_lshlrev_b32_e32 v228, 16, v221
	v_add_f32_e32 v82, v82, v228
	v_and_b32_e32 v228, 0xffff0000, v221
	v_add_f32_e32 v83, v83, v228
	v_lshlrev_b32_e32 v228, 16, v222
	v_add_f32_e32 v76, v76, v228
	v_and_b32_e32 v228, 0xffff0000, v222
	v_add_f32_e32 v77, v77, v228
	v_lshlrev_b32_e32 v228, 16, v223
	v_add_f32_e32 v78, v78, v228
	v_and_b32_e32 v228, 0xffff0000, v223
	v_add_f32_e32 v79, v79, v228
; __device__ __forceinline__ float b2f(u16 b) { return __uint_as_float(((uint32_t)b) << 16); }
; __device__ __forceinline__ float sigmoidf_(float x) { return 1.0f / (1.0f + __expf(-x)); }
; __device__ __forceinline__ void gemm_phase(const Ctx& cx, const GemmArgs& g_, char* shm) {
;     ...
;               const uint2 gv = *(const uint2*)(g.gate + (size_t)tok * NP + n0);
;               float v0 = sigmoidf_(b2f((u16)(gv.x & 0xffff))) * a[0], v1 = sigmoidf_(b2f((u16)(gv.x >> 16))) * a[1];
;               float v2 = sigmoidf_(b2f((u16)(gv.y & 0xffff))) * a[2], v3 = sigmoidf_(b2f((u16)(gv.y >> 16))) * a[3];
;               uint2* mp = (uint2*)(g.outb + (size_t)tok * DM + n0);
;               if (g.epi != EPI_BR0) {
;                 const uint2 pv = *mp;
;                 v0 += b2f((u16)(pv.x & 0xffff)); v1 += b2f((u16)(pv.x >> 16));
;                 v2 += b2f((u16)(pv.y & 0xffff)); v3 += b2f((u16)(pv.y >> 16));
;               }
;               uint2 o; o.x = pack2(v0, v1); o.y = pack2(v2, v3);
;               *mp = o;
.Lmy_br_nopv_add_3_0:
	v_cvt_pk_bf16_f32 v236, v80, v81
	v_cvt_pk_bf16_f32 v237, v82, v83
	v_cvt_pk_bf16_f32 v238, v76, v77
	v_cvt_pk_bf16_f32 v239, v78, v79
	s_nop 1
	v_permlane16_swap_b32_e32 v236, v238
	v_permlane16_swap_b32_e32 v237, v239
	v_lshlrev_b32_e32 v228, 16, v216
	v_mul_f32_e32 v228, 0xbfb8aa3b, v228
	v_exp_f32_e32 v229, v228
	s_nop 0
	v_add_f32_e32 v229, 1.0, v229
	s_nop 0
	v_div_scale_f32 v230, s[2:3], v229, v229, 1.0
	v_rcp_f32_e32 v231, v230
	s_nop 0
	v_fma_f32 v232, -v230, v231, 1.0
	v_fmac_f32_e32 v231, v232, v231
	v_div_scale_f32 v233, vcc, 1.0, v229, 1.0
	v_mul_f32_e32 v234, v233, v231
	v_fma_f32 v235, -v230, v234, v233
	v_fmac_f32_e32 v234, v235, v231
	v_fma_f32 v230, -v230, v234, v233
	v_div_fmas_f32 v230, v230, v231, v234
	v_div_fixup_f32 v230, v230, v229, 1.0
	v_mul_f32_e32 v72, v72, v230
	v_and_b32_e32 v228, 0xffff0000, v216
	v_mul_f32_e32 v228, 0xbfb8aa3b, v228
	v_exp_f32_e32 v229, v228
	s_nop 0
	v_add_f32_e32 v229, 1.0, v229
	s_nop 0
	v_div_scale_f32 v230, s[2:3], v229, v229, 1.0
	v_rcp_f32_e32 v231, v230
	s_nop 0
	v_fma_f32 v232, -v230, v231, 1.0
	v_fmac_f32_e32 v231, v232, v231
	v_div_scale_f32 v233, vcc, 1.0, v229, 1.0
	v_mul_f32_e32 v234, v233, v231
	v_fma_f32 v235, -v230, v234, v233
	v_fmac_f32_e32 v234, v235, v231
	v_fma_f32 v230, -v230, v234, v233
	v_div_fmas_f32 v230, v230, v231, v234
	v_div_fixup_f32 v230, v230, v229, 1.0
	v_mul_f32_e32 v73, v73, v230
	v_lshlrev_b32_e32 v228, 16, v217
	v_mul_f32_e32 v228, 0xbfb8aa3b, v228
	v_exp_f32_e32 v229, v228
	s_nop 0
	v_add_f32_e32 v229, 1.0, v229
	s_nop 0
	v_div_scale_f32 v230, s[2:3], v229, v229, 1.0
	v_rcp_f32_e32 v231, v230
	s_nop 0
	v_fma_f32 v232, -v230, v231, 1.0
	v_fmac_f32_e32 v231, v232, v231
	v_div_scale_f32 v233, vcc, 1.0, v229, 1.0
	v_mul_f32_e32 v234, v233, v231
	v_fma_f32 v235, -v230, v234, v233
	v_fmac_f32_e32 v234, v235, v231
	v_fma_f32 v230, -v230, v234, v233
	v_div_fmas_f32 v230, v230, v231, v234
	v_div_fixup_f32 v230, v230, v229, 1.0
	v_mul_f32_e32 v74, v74, v230
	v_and_b32_e32 v228, 0xffff0000, v217
	v_mul_f32_e32 v228, 0xbfb8aa3b, v228
	v_exp_f32_e32 v229, v228
	s_nop 0
	v_add_f32_e32 v229, 1.0, v229
	s_nop 0
	v_div_scale_f32 v230, s[2:3], v229, v229, 1.0
	v_rcp_f32_e32 v231, v230
	s_nop 0
	v_fma_f32 v232, -v230, v231, 1.0
	v_fmac_f32_e32 v231, v232, v231
	v_div_scale_f32 v233, vcc, 1.0, v229, 1.0
	v_mul_f32_e32 v234, v233, v231
	v_fma_f32 v235, -v230, v234, v233
	v_fmac_f32_e32 v234, v235, v231
	v_fma_f32 v230, -v230, v234, v233
	v_div_fmas_f32 v230, v230, v231, v234
	v_div_fixup_f32 v230, v230, v229, 1.0
	v_mul_f32_e32 v75, v75, v230
	v_lshlrev_b32_e32 v228, 16, v218
	v_mul_f32_e32 v228, 0xbfb8aa3b, v228
	v_exp_f32_e32 v229, v228
	s_nop 0
	v_add_f32_e32 v229, 1.0, v229
	s_nop 0
	v_div_scale_f32 v230, s[2:3], v229, v229, 1.0
	v_rcp_f32_e32 v231, v230
	s_nop 0
	v_fma_f32 v232, -v230, v231, 1.0
	v_fmac_f32_e32 v231, v232, v231
	v_div_scale_f32 v233, vcc, 1.0, v229, 1.0
	v_mul_f32_e32 v234, v233, v231
	v_fma_f32 v235, -v230, v234, v233
	v_fmac_f32_e32 v234, v235, v231
	v_fma_f32 v230, -v230, v234, v233
	v_div_fmas_f32 v230, v230, v231, v234
	v_div_fixup_f32 v230, v230, v229, 1.0
	v_mul_f32_e32 v68, v68, v230
	v_and_b32_e32 v228, 0xffff0000, v218
	v_mul_f32_e32 v228, 0xbfb8aa3b, v228
	v_exp_f32_e32 v229, v228
	s_nop 0
	v_add_f32_e32 v229, 1.0, v229
	s_nop 0
	v_div_scale_f32 v230, s[2:3], v229, v229, 1.0
	v_rcp_f32_e32 v231, v230
	s_nop 0
	v_fma_f32 v232, -v230, v231, 1.0
	v_fmac_f32_e32 v231, v232, v231
	v_div_scale_f32 v233, vcc, 1.0, v229, 1.0
	v_mul_f32_e32 v234, v233, v231
	v_fma_f32 v235, -v230, v234, v233
	v_fmac_f32_e32 v234, v235, v231
	v_fma_f32 v230, -v230, v234, v233
	v_div_fmas_f32 v230, v230, v231, v234
	v_div_fixup_f32 v230, v230, v229, 1.0
	v_mul_f32_e32 v69, v69, v230
	v_lshlrev_b32_e32 v228, 16, v219
	v_mul_f32_e32 v228, 0xbfb8aa3b, v228
	v_exp_f32_e32 v229, v228
	s_nop 0
	v_add_f32_e32 v229, 1.0, v229
	s_nop 0
	v_div_scale_f32 v230, s[2:3], v229, v229, 1.0
	v_rcp_f32_e32 v231, v230
	s_nop 0
	v_fma_f32 v232, -v230, v231, 1.0
	v_fmac_f32_e32 v231, v232, v231
	v_div_scale_f32 v233, vcc, 1.0, v229, 1.0
	v_mul_f32_e32 v234, v233, v231
	v_fma_f32 v235, -v230, v234, v233
	v_fmac_f32_e32 v234, v235, v231
	v_fma_f32 v230, -v230, v234, v233
	v_div_fmas_f32 v230, v230, v231, v234
	v_div_fixup_f32 v230, v230, v229, 1.0
	v_mul_f32_e32 v70, v70, v230
	v_and_b32_e32 v228, 0xffff0000, v219
	v_mul_f32_e32 v228, 0xbfb8aa3b, v228
	v_exp_f32_e32 v229, v228
	s_nop 0
	v_add_f32_e32 v229, 1.0, v229
	s_nop 0
	v_div_scale_f32 v230, s[2:3], v229, v229, 1.0
	v_rcp_f32_e32 v231, v230
	s_nop 0
	v_fma_f32 v232, -v230, v231, 1.0
	v_fmac_f32_e32 v231, v232, v231
	v_div_scale_f32 v233, vcc, 1.0, v229, 1.0
	v_mul_f32_e32 v234, v233, v231
	v_fma_f32 v235, -v230, v234, v233
	v_fmac_f32_e32 v234, v235, v231
	v_fma_f32 v230, -v230, v234, v233
	v_div_fmas_f32 v230, v230, v231, v234
	v_div_fixup_f32 v230, v230, v229, 1.0
	v_mul_f32_e32 v71, v71, v230
	s_and_b64 vcc, exec, s[44:45]
	s_cbranch_vccz .Lmy_br_nopv_add_3_1
	v_lshlrev_b32_e32 v228, 16, v224
	v_add_f32_e32 v72, v72, v228
	v_and_b32_e32 v228, 0xffff0000, v224
	v_add_f32_e32 v73, v73, v228
	v_lshlrev_b32_e32 v228, 16, v225
	v_add_f32_e32 v74, v74, v228
	v_and_b32_e32 v228, 0xffff0000, v225
	v_add_f32_e32 v75, v75, v228
	v_lshlrev_b32_e32 v228, 16, v226
	v_add_f32_e32 v68, v68, v228
	v_and_b32_e32 v228, 0xffff0000, v226
	v_add_f32_e32 v69, v69, v228
	v_lshlrev_b32_e32 v228, 16, v227
	v_add_f32_e32 v70, v70, v228
	v_and_b32_e32 v228, 0xffff0000, v227
	v_add_f32_e32 v71, v71, v228
; __device__ __forceinline__ float b2f(u16 b) { return __uint_as_float(((uint32_t)b) << 16); }
; __device__ __forceinline__ float sigmoidf_(float x) { return 1.0f / (1.0f + __expf(-x)); }
; __device__ __forceinline__ void gemm_phase(const Ctx& cx, const GemmArgs& g_, char* shm) {
;     ...
;               const uint2 gv = *(const uint2*)(g.gate + (size_t)tok * NP + n0);
;               float v0 = sigmoidf_(b2f((u16)(gv.x & 0xffff))) * a[0], v1 = sigmoidf_(b2f((u16)(gv.x >> 16))) * a[1];
;               float v2 = sigmoidf_(b2f((u16)(gv.y & 0xffff))) * a[2], v3 = sigmoidf_(b2f((u16)(gv.y >> 16))) * a[3];
;               uint2* mp = (uint2*)(g.outb + (size_t)tok * DM + n0);
;               if (g.epi != EPI_BR0) {
;                 const uint2 pv = *mp;
;                 v0 += b2f((u16)(pv.x & 0xffff)); v1 += b2f((u16)(pv.x >> 16));
;                 v2 += b2f((u16)(pv.y & 0xffff)); v3 += b2f((u16)(pv.y >> 16));
;               }
;               uint2 o; o.x = pack2(v0, v1); o.y = pack2(v2, v3);
;               *mp = o;
.Lmy_br_nopv_add_3_1:
	v_cvt_pk_bf16_f32 v240, v72, v73
	v_cvt_pk_bf16_f32 v241, v74, v75
	v_cvt_pk_bf16_f32 v242, v68, v69
	v_cvt_pk_bf16_f32 v243, v70, v71
	s_nop 1
	v_permlane16_swap_b32_e32 v240, v242
	v_permlane16_swap_b32_e32 v241, v243
	v_mov_b32_e32 v244, v240
	v_mov_b32_e32 v245, v241
	v_mov_b32_e32 v246, v242
	v_mov_b32_e32 v247, v243
	v_mov_b32_dpp v240, v236 row_ror:8 row_mask:0xf bank_mask:0x3
	v_mov_b32_dpp v241, v237 row_ror:8 row_mask:0xf bank_mask:0x3
	v_mov_b32_dpp v242, v238 row_ror:8 row_mask:0xf bank_mask:0x3
	v_mov_b32_dpp v243, v239 row_ror:8 row_mask:0xf bank_mask:0x3
	v_mov_b32_dpp v236, v244 row_ror:8 row_mask:0xf bank_mask:0xc
	v_mov_b32_dpp v237, v245 row_ror:8 row_mask:0xf bank_mask:0xc
	v_mov_b32_dpp v238, v246 row_ror:8 row_mask:0xf bank_mask:0xc
	v_mov_b32_dpp v239, v247 row_ror:8 row_mask:0xf bank_mask:0xc
	global_store_dwordx4 v[188:189], v[236:239], off offset:288
	global_store_dwordx4 v[190:191], v[240:243], off offset:288
	s_nop 1
	v_lshl_add_u64 v[188:189], v[184:185], 0, s[10:11]
	v_lshl_add_u64 v[190:191], v[188:189], 0, s[6:7]
	v_add_u32_e32 v195, 128, v194
	v_mov_b64_e32 v[244:245], s[22:23]
	v_mad_i64_i32 v[244:245], s[4:5], v195, s76, v[244:245]
	v_lshl_add_u64 v[244:245], v[186:187], 1, v[244:245]
	global_load_dwordx2 v[212:213], v[244:245], off offset:256
	global_load_dwordx2 v[214:215], v[244:245], off offset:288
	global_load_dwordx2 v[216:217], v[244:245], off offset:320
	global_load_dwordx2 v[218:219], v[244:245], off offset:352
	s_and_b64 vcc, exec, s[44:45]
	s_cbranch_vccz .Lmy_br_nopv_ld_5
	v_mov_b32_e32 v192, v195
	v_ashrrev_i32_e32 v193, 31, v195
	v_lshlrev_b64 v[192:193], 12, v[192:193]
	v_lshl_add_u64 v[192:193], s[20:21], 0, v[192:193]
	v_lshl_add_u64 v[192:193], v[186:187], 1, v[192:193]
	global_load_dwordx2 v[220:221], v[192:193], off offset:256
	global_load_dwordx2 v[222:223], v[192:193], off offset:288
	global_load_dwordx2 v[224:225], v[192:193], off offset:320
	global_load_dwordx2 v[226:227], v[192:193], off offset:352

; __device__ __forceinline__ float b2f(u16 b) { return __uint_as_float(((uint32_t)b) << 16); }
; __device__ __forceinline__ float sigmoidf_(float x) { return 1.0f / (1.0f + __expf(-x)); }
; __device__ __forceinline__ void gemm_phase(const Ctx& cx, const GemmArgs& g_, char* shm) {
;     ...
;               const uint2 gv = *(const uint2*)(g.gate + (size_t)tok * NP + n0);
;               float v0 = sigmoidf_(b2f((u16)(gv.x & 0xffff))) * a[0], v1 = sigmoidf_(b2f((u16)(gv.x >> 16))) * a[1];
;               float v2 = sigmoidf_(b2f((u16)(gv.y & 0xffff))) * a[2], v3 = sigmoidf_(b2f((u16)(gv.y >> 16))) * a[3];
;               uint2* mp = (uint2*)(g.outb + (size_t)tok * DM + n0);
;               if (g.epi != EPI_BR0) {
;                 const uint2 pv = *mp;
;                 v0 += b2f((u16)(pv.x & 0xffff)); v1 += b2f((u16)(pv.x >> 16));
;                 v2 += b2f((u16)(pv.y & 0xffff)); v3 += b2f((u16)(pv.y >> 16));
;               }
;               uint2 o; o.x = pack2(v0, v1); o.y = pack2(v2, v3);
;               *mp = o;
.Lmy_br_wj_4:
	v_lshlrev_b32_e32 v228, 16, v196
	v_mul_f32_e32 v228, 0xbfb8aa3b, v228
	v_exp_f32_e32 v229, v228
	s_nop 0
	v_add_f32_e32 v229, 1.0, v229
	s_nop 0
	v_div_scale_f32 v230, s[2:3], v229, v229, 1.0
	v_rcp_f32_e32 v231, v230
	s_nop 0
	v_fma_f32 v232, -v230, v231, 1.0
	v_fmac_f32_e32 v231, v232, v231
	v_div_scale_f32 v233, vcc, 1.0, v229, 1.0
	v_mul_f32_e32 v234, v233, v231
	v_fma_f32 v235, -v230, v234, v233
	v_fmac_f32_e32 v234, v235, v231
	v_fma_f32 v230, -v230, v234, v233
	v_div_fmas_f32 v230, v230, v231, v234
	v_div_fixup_f32 v230, v230, v229, 1.0
	v_mul_f32_e32 v64, v64, v230
	v_and_b32_e32 v228, 0xffff0000, v196
	v_mul_f32_e32 v228, 0xbfb8aa3b, v228
	v_exp_f32_e32 v229, v228
	s_nop 0
	v_add_f32_e32 v229, 1.0, v229
	s_nop 0
	v_div_scale_f32 v230, s[2:3], v229, v229, 1.0
	v_rcp_f32_e32 v231, v230
	s_nop 0
	v_fma_f32 v232, -v230, v231, 1.0
	v_fmac_f32_e32 v231, v232, v231
	v_div_scale_f32 v233, vcc, 1.0, v229, 1.0
	v_mul_f32_e32 v234, v233, v231
	v_fma_f32 v235, -v230, v234, v233
	v_fmac_f32_e32 v234, v235, v231
	v_fma_f32 v230, -v230, v234, v233
	v_div_fmas_f32 v230, v230, v231, v234
	v_div_fixup_f32 v230, v230, v229, 1.0
	v_mul_f32_e32 v65, v65, v230
	v_lshlrev_b32_e32 v228, 16, v197
	v_mul_f32_e32 v228, 0xbfb8aa3b, v228
	v_exp_f32_e32 v229, v228
	s_nop 0
	v_add_f32_e32 v229, 1.0, v229
	s_nop 0
	v_div_scale_f32 v230, s[2:3], v229, v229, 1.0
	v_rcp_f32_e32 v231, v230
	s_nop 0
	v_fma_f32 v232, -v230, v231, 1.0
	v_fmac_f32_e32 v231, v232, v231
	v_div_scale_f32 v233, vcc, 1.0, v229, 1.0
	v_mul_f32_e32 v234, v233, v231
	v_fma_f32 v235, -v230, v234, v233
	v_fmac_f32_e32 v234, v235, v231
	v_fma_f32 v230, -v230, v234, v233
	v_div_fmas_f32 v230, v230, v231, v234
	v_div_fixup_f32 v230, v230, v229, 1.0
	v_mul_f32_e32 v66, v66, v230
	v_and_b32_e32 v228, 0xffff0000, v197
	v_mul_f32_e32 v228, 0xbfb8aa3b, v228
	v_exp_f32_e32 v229, v228
	s_nop 0
	v_add_f32_e32 v229, 1.0, v229
	s_nop 0
	v_div_scale_f32 v230, s[2:3], v229, v229, 1.0
	v_rcp_f32_e32 v231, v230
	s_nop 0
	v_fma_f32 v232, -v230, v231, 1.0
	v_fmac_f32_e32 v231, v232, v231
	v_div_scale_f32 v233, vcc, 1.0, v229, 1.0
	v_mul_f32_e32 v234, v233, v231
	v_fma_f32 v235, -v230, v234, v233
	v_fmac_f32_e32 v234, v235, v231
	v_fma_f32 v230, -v230, v234, v233
	v_div_fmas_f32 v230, v230, v231, v234
	v_div_fixup_f32 v230, v230, v229, 1.0
	v_mul_f32_e32 v67, v67, v230
	v_lshlrev_b32_e32 v228, 16, v198
	v_mul_f32_e32 v228, 0xbfb8aa3b, v228
	v_exp_f32_e32 v229, v228
	s_nop 0
	v_add_f32_e32 v229, 1.0, v229
	s_nop 0
	v_div_scale_f32 v230, s[2:3], v229, v229, 1.0
	v_rcp_f32_e32 v231, v230
	s_nop 0
	v_fma_f32 v232, -v230, v231, 1.0
	v_fmac_f32_e32 v231, v232, v231
	v_div_scale_f32 v233, vcc, 1.0, v229, 1.0
	v_mul_f32_e32 v234, v233, v231
	v_fma_f32 v235, -v230, v234, v233
	v_fmac_f32_e32 v234, v235, v231
	v_fma_f32 v230, -v230, v234, v233
	v_div_fmas_f32 v230, v230, v231, v234
	v_div_fixup_f32 v230, v230, v229, 1.0
	v_mul_f32_e32 v60, v60, v230
	v_and_b32_e32 v228, 0xffff0000, v198
	v_mul_f32_e32 v228, 0xbfb8aa3b, v228
	v_exp_f32_e32 v229, v228
	s_nop 0
	v_add_f32_e32 v229, 1.0, v229
	s_nop 0
	v_div_scale_f32 v230, s[2:3], v229, v229, 1.0
	v_rcp_f32_e32 v231, v230
	s_nop 0
	v_fma_f32 v232, -v230, v231, 1.0
	v_fmac_f32_e32 v231, v232, v231
	v_div_scale_f32 v233, vcc, 1.0, v229, 1.0
	v_mul_f32_e32 v234, v233, v231
	v_fma_f32 v235, -v230, v234, v233
	v_fmac_f32_e32 v234, v235, v231
	v_fma_f32 v230, -v230, v234, v233
	v_div_fmas_f32 v230, v230, v231, v234
	v_div_fixup_f32 v230, v230, v229, 1.0
	v_mul_f32_e32 v61, v61, v230
	v_lshlrev_b32_e32 v228, 16, v199
	v_mul_f32_e32 v228, 0xbfb8aa3b, v228
	v_exp_f32_e32 v229, v228
	s_nop 0
	v_add_f32_e32 v229, 1.0, v229
	s_nop 0
	v_div_scale_f32 v230, s[2:3], v229, v229, 1.0
	v_rcp_f32_e32 v231, v230
	s_nop 0
	v_fma_f32 v232, -v230, v231, 1.0
	v_fmac_f32_e32 v231, v232, v231
	v_div_scale_f32 v233, vcc, 1.0, v229, 1.0
	v_mul_f32_e32 v234, v233, v231
	v_fma_f32 v235, -v230, v234, v233
	v_fmac_f32_e32 v234, v235, v231
	v_fma_f32 v230, -v230, v234, v233
	v_div_fmas_f32 v230, v230, v231, v234
	v_div_fixup_f32 v230, v230, v229, 1.0
	v_mul_f32_e32 v62, v62, v230
	v_and_b32_e32 v228, 0xffff0000, v199
	v_mul_f32_e32 v228, 0xbfb8aa3b, v228
	v_exp_f32_e32 v229, v228
	s_nop 0
	v_add_f32_e32 v229, 1.0, v229
	s_nop 0
	v_div_scale_f32 v230, s[2:3], v229, v229, 1.0
	v_rcp_f32_e32 v231, v230
	s_nop 0
	v_fma_f32 v232, -v230, v231, 1.0
	v_fmac_f32_e32 v231, v232, v231
	v_div_scale_f32 v233, vcc, 1.0, v229, 1.0
	v_mul_f32_e32 v234, v233, v231
	v_fma_f32 v235, -v230, v234, v233
	v_fmac_f32_e32 v234, v235, v231
	v_fma_f32 v230, -v230, v234, v233
	v_div_fmas_f32 v230, v230, v231, v234
	v_div_fixup_f32 v230, v230, v229, 1.0
	v_mul_f32_e32 v63, v63, v230
	s_and_b64 vcc, exec, s[44:45]
	s_cbranch_vccz .Lmy_br_nopv_add_4_0
	v_lshlrev_b32_e32 v228, 16, v204
	v_add_f32_e32 v64, v64, v228
	v_and_b32_e32 v228, 0xffff0000, v204
	v_add_f32_e32 v65, v65, v228
	v_lshlrev_b32_e32 v228, 16, v205
	v_add_f32_e32 v66, v66, v228
	v_and_b32_e32 v228, 0xffff0000, v205
	v_add_f32_e32 v67, v67, v228
	v_lshlrev_b32_e32 v228, 16, v206
	v_add_f32_e32 v60, v60, v228
	v_and_b32_e32 v228, 0xffff0000, v206
	v_add_f32_e32 v61, v61, v228
	v_lshlrev_b32_e32 v228, 16, v207
	v_add_f32_e32 v62, v62, v228
	v_and_b32_e32 v228, 0xffff0000, v207
	v_add_f32_e32 v63, v63, v228
; __device__ __forceinline__ float b2f(u16 b) { return __uint_as_float(((uint32_t)b) << 16); }
; __device__ __forceinline__ float sigmoidf_(float x) { return 1.0f / (1.0f + __expf(-x)); }
; __device__ __forceinline__ void gemm_phase(const Ctx& cx, const GemmArgs& g_, char* shm) {
;     ...
;               const uint2 gv = *(const uint2*)(g.gate + (size_t)tok * NP + n0);
;               float v0 = sigmoidf_(b2f((u16)(gv.x & 0xffff))) * a[0], v1 = sigmoidf_(b2f((u16)(gv.x >> 16))) * a[1];
;               float v2 = sigmoidf_(b2f((u16)(gv.y & 0xffff))) * a[2], v3 = sigmoidf_(b2f((u16)(gv.y >> 16))) * a[3];
;               uint2* mp = (uint2*)(g.outb + (size_t)tok * DM + n0);
;               if (g.epi != EPI_BR0) {
;                 const uint2 pv = *mp;
;                 v0 += b2f((u16)(pv.x & 0xffff)); v1 += b2f((u16)(pv.x >> 16));
;                 v2 += b2f((u16)(pv.y & 0xffff)); v3 += b2f((u16)(pv.y >> 16));
;               }
;               uint2 o; o.x = pack2(v0, v1); o.y = pack2(v2, v3);
;               *mp = o;
.Lmy_br_nopv_add_4_0:
	v_cvt_pk_bf16_f32 v236, v64, v65
	v_cvt_pk_bf16_f32 v237, v66, v67
	v_cvt_pk_bf16_f32 v238, v60, v61
	v_cvt_pk_bf16_f32 v239, v62, v63
	s_nop 1
	v_permlane16_swap_b32_e32 v236, v238
	v_permlane16_swap_b32_e32 v237, v239
	v_lshlrev_b32_e32 v228, 16, v200
	v_mul_f32_e32 v228, 0xbfb8aa3b, v228
	v_exp_f32_e32 v229, v228
	s_nop 0
	v_add_f32_e32 v229, 1.0, v229
	s_nop 0
	v_div_scale_f32 v230, s[2:3], v229, v229, 1.0
	v_rcp_f32_e32 v231, v230
	s_nop 0
	v_fma_f32 v232, -v230, v231, 1.0
	v_fmac_f32_e32 v231, v232, v231
	v_div_scale_f32 v233, vcc, 1.0, v229, 1.0
	v_mul_f32_e32 v234, v233, v231
	v_fma_f32 v235, -v230, v234, v233
	v_fmac_f32_e32 v234, v235, v231
	v_fma_f32 v230, -v230, v234, v233
	v_div_fmas_f32 v230, v230, v231, v234
	v_div_fixup_f32 v230, v230, v229, 1.0
	v_mul_f32_e32 v56, v56, v230
	v_and_b32_e32 v228, 0xffff0000, v200
	v_mul_f32_e32 v228, 0xbfb8aa3b, v228
	v_exp_f32_e32 v229, v228
	s_nop 0
	v_add_f32_e32 v229, 1.0, v229
	s_nop 0
	v_div_scale_f32 v230, s[2:3], v229, v229, 1.0
	v_rcp_f32_e32 v231, v230
	s_nop 0
	v_fma_f32 v232, -v230, v231, 1.0
	v_fmac_f32_e32 v231, v232, v231
	v_div_scale_f32 v233, vcc, 1.0, v229, 1.0
	v_mul_f32_e32 v234, v233, v231
	v_fma_f32 v235, -v230, v234, v233
	v_fmac_f32_e32 v234, v235, v231
	v_fma_f32 v230, -v230, v234, v233
	v_div_fmas_f32 v230, v230, v231, v234
	v_div_fixup_f32 v230, v230, v229, 1.0
	v_mul_f32_e32 v57, v57, v230
	v_lshlrev_b32_e32 v228, 16, v201
	v_mul_f32_e32 v228, 0xbfb8aa3b, v228
	v_exp_f32_e32 v229, v228
	s_nop 0
	v_add_f32_e32 v229, 1.0, v229
	s_nop 0
	v_div_scale_f32 v230, s[2:3], v229, v229, 1.0
	v_rcp_f32_e32 v231, v230
	s_nop 0
	v_fma_f32 v232, -v230, v231, 1.0
	v_fmac_f32_e32 v231, v232, v231
	v_div_scale_f32 v233, vcc, 1.0, v229, 1.0
	v_mul_f32_e32 v234, v233, v231
	v_fma_f32 v235, -v230, v234, v233
	v_fmac_f32_e32 v234, v235, v231
	v_fma_f32 v230, -v230, v234, v233
	v_div_fmas_f32 v230, v230, v231, v234
	v_div_fixup_f32 v230, v230, v229, 1.0
	v_mul_f32_e32 v58, v58, v230
	v_and_b32_e32 v228, 0xffff0000, v201
	v_mul_f32_e32 v228, 0xbfb8aa3b, v228
	v_exp_f32_e32 v229, v228
	s_nop 0
	v_add_f32_e32 v229, 1.0, v229
	s_nop 0
	v_div_scale_f32 v230, s[2:3], v229, v229, 1.0
	v_rcp_f32_e32 v231, v230
	s_nop 0
	v_fma_f32 v232, -v230, v231, 1.0
	v_fmac_f32_e32 v231, v232, v231
	v_div_scale_f32 v233, vcc, 1.0, v229, 1.0
	v_mul_f32_e32 v234, v233, v231
	v_fma_f32 v235, -v230, v234, v233
	v_fmac_f32_e32 v234, v235, v231
	v_fma_f32 v230, -v230, v234, v233
	v_div_fmas_f32 v230, v230, v231, v234
	v_div_fixup_f32 v230, v230, v229, 1.0
	v_mul_f32_e32 v59, v59, v230
	v_lshlrev_b32_e32 v228, 16, v202
	v_mul_f32_e32 v228, 0xbfb8aa3b, v228
	v_exp_f32_e32 v229, v228
	s_nop 0
	v_add_f32_e32 v229, 1.0, v229
	s_nop 0
	v_div_scale_f32 v230, s[2:3], v229, v229, 1.0
	v_rcp_f32_e32 v231, v230
	s_nop 0
	v_fma_f32 v232, -v230, v231, 1.0
	v_fmac_f32_e32 v231, v232, v231
	v_div_scale_f32 v233, vcc, 1.0, v229, 1.0
	v_mul_f32_e32 v234, v233, v231
	v_fma_f32 v235, -v230, v234, v233
	v_fmac_f32_e32 v234, v235, v231
	v_fma_f32 v230, -v230, v234, v233
	v_div_fmas_f32 v230, v230, v231, v234
	v_div_fixup_f32 v230, v230, v229, 1.0
	v_mul_f32_e32 v52, v52, v230
	v_and_b32_e32 v228, 0xffff0000, v202
	v_mul_f32_e32 v228, 0xbfb8aa3b, v228
	v_exp_f32_e32 v229, v228
	s_nop 0
	v_add_f32_e32 v229, 1.0, v229
	s_nop 0
	v_div_scale_f32 v230, s[2:3], v229, v229, 1.0
	v_rcp_f32_e32 v231, v230
	s_nop 0
	v_fma_f32 v232, -v230, v231, 1.0
	v_fmac_f32_e32 v231, v232, v231
	v_div_scale_f32 v233, vcc, 1.0, v229, 1.0
	v_mul_f32_e32 v234, v233, v231
	v_fma_f32 v235, -v230, v234, v233
	v_fmac_f32_e32 v234, v235, v231
	v_fma_f32 v230, -v230, v234, v233
	v_div_fmas_f32 v230, v230, v231, v234
	v_div_fixup_f32 v230, v230, v229, 1.0
	v_mul_f32_e32 v53, v53, v230
	v_lshlrev_b32_e32 v228, 16, v203
	v_mul_f32_e32 v228, 0xbfb8aa3b, v228
	v_exp_f32_e32 v229, v228
	s_nop 0
	v_add_f32_e32 v229, 1.0, v229
	s_nop 0
	v_div_scale_f32 v230, s[2:3], v229, v229, 1.0
	v_rcp_f32_e32 v231, v230
	s_nop 0
	v_fma_f32 v232, -v230, v231, 1.0
	v_fmac_f32_e32 v231, v232, v231
	v_div_scale_f32 v233, vcc, 1.0, v229, 1.0
	v_mul_f32_e32 v234, v233, v231
	v_fma_f32 v235, -v230, v234, v233
	v_fmac_f32_e32 v234, v235, v231
	v_fma_f32 v230, -v230, v234, v233
	v_div_fmas_f32 v230, v230, v231, v234
	v_div_fixup_f32 v230, v230, v229, 1.0
	v_mul_f32_e32 v54, v54, v230
	v_and_b32_e32 v228, 0xffff0000, v203
	v_mul_f32_e32 v228, 0xbfb8aa3b, v228
	v_exp_f32_e32 v229, v228
	s_nop 0
	v_add_f32_e32 v229, 1.0, v229
	s_nop 0
	v_div_scale_f32 v230, s[2:3], v229, v229, 1.0
	v_rcp_f32_e32 v231, v230
	s_nop 0
	v_fma_f32 v232, -v230, v231, 1.0
	v_fmac_f32_e32 v231, v232, v231
	v_div_scale_f32 v233, vcc, 1.0, v229, 1.0
	v_mul_f32_e32 v234, v233, v231
	v_fma_f32 v235, -v230, v234, v233
	v_fmac_f32_e32 v234, v235, v231
	v_fma_f32 v230, -v230, v234, v233
	v_div_fmas_f32 v230, v230, v231, v234
	v_div_fixup_f32 v230, v230, v229, 1.0
	v_mul_f32_e32 v55, v55, v230
	s_and_b64 vcc, exec, s[44:45]
	s_cbranch_vccz .Lmy_br_nopv_add_4_1
	v_lshlrev_b32_e32 v228, 16, v208
	v_add_f32_e32 v56, v56, v228
	v_and_b32_e32 v228, 0xffff0000, v208
	v_add_f32_e32 v57, v57, v228
	v_lshlrev_b32_e32 v228, 16, v209
	v_add_f32_e32 v58, v58, v228
	v_and_b32_e32 v228, 0xffff0000, v209
	v_add_f32_e32 v59, v59, v228
	v_lshlrev_b32_e32 v228, 16, v210
	v_add_f32_e32 v52, v52, v228
	v_and_b32_e32 v228, 0xffff0000, v210
	v_add_f32_e32 v53, v53, v228
	v_lshlrev_b32_e32 v228, 16, v211
	v_add_f32_e32 v54, v54, v228
	v_and_b32_e32 v228, 0xffff0000, v211
	v_add_f32_e32 v55, v55, v228
; __device__ __forceinline__ float b2f(u16 b) { return __uint_as_float(((uint32_t)b) << 16); }
; __device__ __forceinline__ float sigmoidf_(float x) { return 1.0f / (1.0f + __expf(-x)); }
; __device__ __forceinline__ void gemm_phase(const Ctx& cx, const GemmArgs& g_, char* shm) {
;     ...
;               const uint2 gv = *(const uint2*)(g.gate + (size_t)tok * NP + n0);
;               float v0 = sigmoidf_(b2f((u16)(gv.x & 0xffff))) * a[0], v1 = sigmoidf_(b2f((u16)(gv.x >> 16))) * a[1];
;               float v2 = sigmoidf_(b2f((u16)(gv.y & 0xffff))) * a[2], v3 = sigmoidf_(b2f((u16)(gv.y >> 16))) * a[3];
;               uint2* mp = (uint2*)(g.outb + (size_t)tok * DM + n0);
;               if (g.epi != EPI_BR0) {
;                 const uint2 pv = *mp;
;                 v0 += b2f((u16)(pv.x & 0xffff)); v1 += b2f((u16)(pv.x >> 16));
;                 v2 += b2f((u16)(pv.y & 0xffff)); v3 += b2f((u16)(pv.y >> 16));
;               }
;               uint2 o; o.x = pack2(v0, v1); o.y = pack2(v2, v3);
;               *mp = o;
.Lmy_br_nopv_add_4_1:
	v_cvt_pk_bf16_f32 v240, v56, v57
	v_cvt_pk_bf16_f32 v241, v58, v59
	v_cvt_pk_bf16_f32 v242, v52, v53
	v_cvt_pk_bf16_f32 v243, v54, v55
	s_nop 1
	v_permlane16_swap_b32_e32 v240, v242
	v_permlane16_swap_b32_e32 v241, v243
	v_mov_b32_e32 v244, v240
	v_mov_b32_e32 v245, v241
	v_mov_b32_e32 v246, v242
	v_mov_b32_e32 v247, v243
	v_mov_b32_dpp v240, v236 row_ror:8 row_mask:0xf bank_mask:0x3
	v_mov_b32_dpp v241, v237 row_ror:8 row_mask:0xf bank_mask:0x3
	v_mov_b32_dpp v242, v238 row_ror:8 row_mask:0xf bank_mask:0x3
	v_mov_b32_dpp v243, v239 row_ror:8 row_mask:0xf bank_mask:0x3
	v_mov_b32_dpp v236, v244 row_ror:8 row_mask:0xf bank_mask:0xc
	v_mov_b32_dpp v237, v245 row_ror:8 row_mask:0xf bank_mask:0xc
	v_mov_b32_dpp v238, v246 row_ror:8 row_mask:0xf bank_mask:0xc
	v_mov_b32_dpp v239, v247 row_ror:8 row_mask:0xf bank_mask:0xc
	global_store_dwordx4 v[188:189], v[236:239], off offset:32
	global_store_dwordx4 v[190:191], v[240:243], off offset:32
	s_nop 1
	v_add_u32_e32 v195, 144, v194
	v_mov_b64_e32 v[244:245], s[22:23]
	v_mad_i64_i32 v[244:245], s[4:5], v195, s76, v[244:245]
	v_lshl_add_u64 v[244:245], v[186:187], 1, v[244:245]
	global_load_dwordx2 v[196:197], v[244:245], off offset:0
	global_load_dwordx2 v[198:199], v[244:245], off offset:32
	global_load_dwordx2 v[200:201], v[244:245], off offset:64
	global_load_dwordx2 v[202:203], v[244:245], off offset:96
	s_and_b64 vcc, exec, s[44:45]
	s_cbranch_vccz .Lmy_br_nopv_ld_6
	v_mov_b32_e32 v192, v195
	v_ashrrev_i32_e32 v193, 31, v195
	v_lshlrev_b64 v[192:193], 12, v[192:193]
	v_lshl_add_u64 v[192:193], s[20:21], 0, v[192:193]
	v_lshl_add_u64 v[192:193], v[186:187], 1, v[192:193]
	global_load_dwordx2 v[204:205], v[192:193], off offset:0
	global_load_dwordx2 v[206:207], v[192:193], off offset:32
	global_load_dwordx2 v[208:209], v[192:193], off offset:64
	global_load_dwordx2 v[210:211], v[192:193], off offset:96

; __device__ __forceinline__ float b2f(u16 b) { return __uint_as_float(((uint32_t)b) << 16); }
; __device__ __forceinline__ float sigmoidf_(float x) { return 1.0f / (1.0f + __expf(-x)); }
; __device__ __forceinline__ void gemm_phase(const Ctx& cx, const GemmArgs& g_, char* shm) {
;     ...
;               const uint2 gv = *(const uint2*)(g.gate + (size_t)tok * NP + n0);
;               float v0 = sigmoidf_(b2f((u16)(gv.x & 0xffff))) * a[0], v1 = sigmoidf_(b2f((u16)(gv.x >> 16))) * a[1];
;               float v2 = sigmoidf_(b2f((u16)(gv.y & 0xffff))) * a[2], v3 = sigmoidf_(b2f((u16)(gv.y >> 16))) * a[3];
;               uint2* mp = (uint2*)(g.outb + (size_t)tok * DM + n0);
;               if (g.epi != EPI_BR0) {
;                 const uint2 pv = *mp;
;                 v0 += b2f((u16)(pv.x & 0xffff)); v1 += b2f((u16)(pv.x >> 16));
;                 v2 += b2f((u16)(pv.y & 0xffff)); v3 += b2f((u16)(pv.y >> 16));
;               }
;               uint2 o; o.x = pack2(v0, v1); o.y = pack2(v2, v3);
;               *mp = o;
.Lmy_br_wj_5:
	v_lshlrev_b32_e32 v228, 16, v212
	v_mul_f32_e32 v228, 0xbfb8aa3b, v228
	v_exp_f32_e32 v229, v228
	s_nop 0
	v_add_f32_e32 v229, 1.0, v229
	s_nop 0
	v_div_scale_f32 v230, s[2:3], v229, v229, 1.0
	v_rcp_f32_e32 v231, v230
	s_nop 0
	v_fma_f32 v232, -v230, v231, 1.0
	v_fmac_f32_e32 v231, v232, v231
	v_div_scale_f32 v233, vcc, 1.0, v229, 1.0
	v_mul_f32_e32 v234, v233, v231
	v_fma_f32 v235, -v230, v234, v233
	v_fmac_f32_e32 v234, v235, v231
	v_fma_f32 v230, -v230, v234, v233
	v_div_fmas_f32 v230, v230, v231, v234
	v_div_fixup_f32 v230, v230, v229, 1.0
	v_mul_f32_e32 v48, v48, v230
	v_and_b32_e32 v228, 0xffff0000, v212
	v_mul_f32_e32 v228, 0xbfb8aa3b, v228
	v_exp_f32_e32 v229, v228
	s_nop 0
	v_add_f32_e32 v229, 1.0, v229
	s_nop 0
	v_div_scale_f32 v230, s[2:3], v229, v229, 1.0
	v_rcp_f32_e32 v231, v230
	s_nop 0
	v_fma_f32 v232, -v230, v231, 1.0
	v_fmac_f32_e32 v231, v232, v231
	v_div_scale_f32 v233, vcc, 1.0, v229, 1.0
	v_mul_f32_e32 v234, v233, v231
	v_fma_f32 v235, -v230, v234, v233
	v_fmac_f32_e32 v234, v235, v231
	v_fma_f32 v230, -v230, v234, v233
	v_div_fmas_f32 v230, v230, v231, v234
	v_div_fixup_f32 v230, v230, v229, 1.0
	v_mul_f32_e32 v49, v49, v230
	v_lshlrev_b32_e32 v228, 16, v213
	v_mul_f32_e32 v228, 0xbfb8aa3b, v228
	v_exp_f32_e32 v229, v228
	s_nop 0
	v_add_f32_e32 v229, 1.0, v229
	s_nop 0
	v_div_scale_f32 v230, s[2:3], v229, v229, 1.0
	v_rcp_f32_e32 v231, v230
	s_nop 0
	v_fma_f32 v232, -v230, v231, 1.0
	v_fmac_f32_e32 v231, v232, v231
	v_div_scale_f32 v233, vcc, 1.0, v229, 1.0
	v_mul_f32_e32 v234, v233, v231
	v_fma_f32 v235, -v230, v234, v233
	v_fmac_f32_e32 v234, v235, v231
	v_fma_f32 v230, -v230, v234, v233
	v_div_fmas_f32 v230, v230, v231, v234
	v_div_fixup_f32 v230, v230, v229, 1.0
	v_mul_f32_e32 v50, v50, v230
	v_and_b32_e32 v228, 0xffff0000, v213
	v_mul_f32_e32 v228, 0xbfb8aa3b, v228
	v_exp_f32_e32 v229, v228
	s_nop 0
	v_add_f32_e32 v229, 1.0, v229
	s_nop 0
	v_div_scale_f32 v230, s[2:3], v229, v229, 1.0
	v_rcp_f32_e32 v231, v230
	s_nop 0
	v_fma_f32 v232, -v230, v231, 1.0
	v_fmac_f32_e32 v231, v232, v231
	v_div_scale_f32 v233, vcc, 1.0, v229, 1.0
	v_mul_f32_e32 v234, v233, v231
	v_fma_f32 v235, -v230, v234, v233
	v_fmac_f32_e32 v234, v235, v231
	v_fma_f32 v230, -v230, v234, v233
	v_div_fmas_f32 v230, v230, v231, v234
	v_div_fixup_f32 v230, v230, v229, 1.0
	v_mul_f32_e32 v51, v51, v230
	v_lshlrev_b32_e32 v228, 16, v214
	v_mul_f32_e32 v228, 0xbfb8aa3b, v228
	v_exp_f32_e32 v229, v228
	s_nop 0
	v_add_f32_e32 v229, 1.0, v229
	s_nop 0
	v_div_scale_f32 v230, s[2:3], v229, v229, 1.0
	v_rcp_f32_e32 v231, v230
	s_nop 0
	v_fma_f32 v232, -v230, v231, 1.0
	v_fmac_f32_e32 v231, v232, v231
	v_div_scale_f32 v233, vcc, 1.0, v229, 1.0
	v_mul_f32_e32 v234, v233, v231
	v_fma_f32 v235, -v230, v234, v233
	v_fmac_f32_e32 v234, v235, v231
	v_fma_f32 v230, -v230, v234, v233
	v_div_fmas_f32 v230, v230, v231, v234
	v_div_fixup_f32 v230, v230, v229, 1.0
	v_mul_f32_e32 v44, v44, v230
	v_and_b32_e32 v228, 0xffff0000, v214
	v_mul_f32_e32 v228, 0xbfb8aa3b, v228
	v_exp_f32_e32 v229, v228
	s_nop 0
	v_add_f32_e32 v229, 1.0, v229
	s_nop 0
	v_div_scale_f32 v230, s[2:3], v229, v229, 1.0
	v_rcp_f32_e32 v231, v230
	s_nop 0
	v_fma_f32 v232, -v230, v231, 1.0
	v_fmac_f32_e32 v231, v232, v231
	v_div_scale_f32 v233, vcc, 1.0, v229, 1.0
	v_mul_f32_e32 v234, v233, v231
	v_fma_f32 v235, -v230, v234, v233
	v_fmac_f32_e32 v234, v235, v231
	v_fma_f32 v230, -v230, v234, v233
	v_div_fmas_f32 v230, v230, v231, v234
	v_div_fixup_f32 v230, v230, v229, 1.0
	v_mul_f32_e32 v45, v45, v230
	v_lshlrev_b32_e32 v228, 16, v215
	v_mul_f32_e32 v228, 0xbfb8aa3b, v228
	v_exp_f32_e32 v229, v228
	s_nop 0
	v_add_f32_e32 v229, 1.0, v229
	s_nop 0
	v_div_scale_f32 v230, s[2:3], v229, v229, 1.0
	v_rcp_f32_e32 v231, v230
	s_nop 0
	v_fma_f32 v232, -v230, v231, 1.0
	v_fmac_f32_e32 v231, v232, v231
	v_div_scale_f32 v233, vcc, 1.0, v229, 1.0
	v_mul_f32_e32 v234, v233, v231
	v_fma_f32 v235, -v230, v234, v233
	v_fmac_f32_e32 v234, v235, v231
	v_fma_f32 v230, -v230, v234, v233
	v_div_fmas_f32 v230, v230, v231, v234
	v_div_fixup_f32 v230, v230, v229, 1.0
	v_mul_f32_e32 v46, v46, v230
	v_and_b32_e32 v228, 0xffff0000, v215
	v_mul_f32_e32 v228, 0xbfb8aa3b, v228
	v_exp_f32_e32 v229, v228
	s_nop 0
	v_add_f32_e32 v229, 1.0, v229
	s_nop 0
	v_div_scale_f32 v230, s[2:3], v229, v229, 1.0
	v_rcp_f32_e32 v231, v230
	s_nop 0
	v_fma_f32 v232, -v230, v231, 1.0
	v_fmac_f32_e32 v231, v232, v231
	v_div_scale_f32 v233, vcc, 1.0, v229, 1.0
	v_mul_f32_e32 v234, v233, v231
	v_fma_f32 v235, -v230, v234, v233
	v_fmac_f32_e32 v234, v235, v231
	v_fma_f32 v230, -v230, v234, v233
	v_div_fmas_f32 v230, v230, v231, v234
	v_div_fixup_f32 v230, v230, v229, 1.0
	v_mul_f32_e32 v47, v47, v230
	s_and_b64 vcc, exec, s[44:45]
	s_cbranch_vccz .Lmy_br_nopv_add_5_0
	v_lshlrev_b32_e32 v228, 16, v220
	v_add_f32_e32 v48, v48, v228
	v_and_b32_e32 v228, 0xffff0000, v220
	v_add_f32_e32 v49, v49, v228
	v_lshlrev_b32_e32 v228, 16, v221
	v_add_f32_e32 v50, v50, v228
	v_and_b32_e32 v228, 0xffff0000, v221
	v_add_f32_e32 v51, v51, v228
	v_lshlrev_b32_e32 v228, 16, v222
	v_add_f32_e32 v44, v44, v228
	v_and_b32_e32 v228, 0xffff0000, v222
	v_add_f32_e32 v45, v45, v228
	v_lshlrev_b32_e32 v228, 16, v223
	v_add_f32_e32 v46, v46, v228
	v_and_b32_e32 v228, 0xffff0000, v223
	v_add_f32_e32 v47, v47, v228
; __device__ __forceinline__ float b2f(u16 b) { return __uint_as_float(((uint32_t)b) << 16); }
; __device__ __forceinline__ float sigmoidf_(float x) { return 1.0f / (1.0f + __expf(-x)); }
; __device__ __forceinline__ void gemm_phase(const Ctx& cx, const GemmArgs& g_, char* shm) {
;     ...
;               const uint2 gv = *(const uint2*)(g.gate + (size_t)tok * NP + n0);
;               float v0 = sigmoidf_(b2f((u16)(gv.x & 0xffff))) * a[0], v1 = sigmoidf_(b2f((u16)(gv.x >> 16))) * a[1];
;               float v2 = sigmoidf_(b2f((u16)(gv.y & 0xffff))) * a[2], v3 = sigmoidf_(b2f((u16)(gv.y >> 16))) * a[3];
;               uint2* mp = (uint2*)(g.outb + (size_t)tok * DM + n0);
;               if (g.epi != EPI_BR0) {
;                 const uint2 pv = *mp;
;                 v0 += b2f((u16)(pv.x & 0xffff)); v1 += b2f((u16)(pv.x >> 16));
;                 v2 += b2f((u16)(pv.y & 0xffff)); v3 += b2f((u16)(pv.y >> 16));
;               }
;               uint2 o; o.x = pack2(v0, v1); o.y = pack2(v2, v3);
;               *mp = o;
.Lmy_br_nopv_add_5_0:
	v_cvt_pk_bf16_f32 v236, v48, v49
	v_cvt_pk_bf16_f32 v237, v50, v51
	v_cvt_pk_bf16_f32 v238, v44, v45
	v_cvt_pk_bf16_f32 v239, v46, v47
	s_nop 1
	v_permlane16_swap_b32_e32 v236, v238
	v_permlane16_swap_b32_e32 v237, v239
	v_lshlrev_b32_e32 v228, 16, v216
	v_mul_f32_e32 v228, 0xbfb8aa3b, v228
	v_exp_f32_e32 v229, v228
	s_nop 0
	v_add_f32_e32 v229, 1.0, v229
	s_nop 0
	v_div_scale_f32 v230, s[2:3], v229, v229, 1.0
	v_rcp_f32_e32 v231, v230
	s_nop 0
	v_fma_f32 v232, -v230, v231, 1.0
	v_fmac_f32_e32 v231, v232, v231
	v_div_scale_f32 v233, vcc, 1.0, v229, 1.0
	v_mul_f32_e32 v234, v233, v231
	v_fma_f32 v235, -v230, v234, v233
	v_fmac_f32_e32 v234, v235, v231
	v_fma_f32 v230, -v230, v234, v233
	v_div_fmas_f32 v230, v230, v231, v234
	v_div_fixup_f32 v230, v230, v229, 1.0
	v_mul_f32_e32 v40, v40, v230
	v_and_b32_e32 v228, 0xffff0000, v216
	v_mul_f32_e32 v228, 0xbfb8aa3b, v228
	v_exp_f32_e32 v229, v228
	s_nop 0
	v_add_f32_e32 v229, 1.0, v229
	s_nop 0
	v_div_scale_f32 v230, s[2:3], v229, v229, 1.0
	v_rcp_f32_e32 v231, v230
	s_nop 0
	v_fma_f32 v232, -v230, v231, 1.0
	v_fmac_f32_e32 v231, v232, v231
	v_div_scale_f32 v233, vcc, 1.0, v229, 1.0
	v_mul_f32_e32 v234, v233, v231
	v_fma_f32 v235, -v230, v234, v233
	v_fmac_f32_e32 v234, v235, v231
	v_fma_f32 v230, -v230, v234, v233
	v_div_fmas_f32 v230, v230, v231, v234
	v_div_fixup_f32 v230, v230, v229, 1.0
	v_mul_f32_e32 v41, v41, v230
	v_lshlrev_b32_e32 v228, 16, v217
	v_mul_f32_e32 v228, 0xbfb8aa3b, v228
	v_exp_f32_e32 v229, v228
	s_nop 0
	v_add_f32_e32 v229, 1.0, v229
	s_nop 0
	v_div_scale_f32 v230, s[2:3], v229, v229, 1.0
	v_rcp_f32_e32 v231, v230
	s_nop 0
	v_fma_f32 v232, -v230, v231, 1.0
	v_fmac_f32_e32 v231, v232, v231
	v_div_scale_f32 v233, vcc, 1.0, v229, 1.0
	v_mul_f32_e32 v234, v233, v231
	v_fma_f32 v235, -v230, v234, v233
	v_fmac_f32_e32 v234, v235, v231
	v_fma_f32 v230, -v230, v234, v233
	v_div_fmas_f32 v230, v230, v231, v234
	v_div_fixup_f32 v230, v230, v229, 1.0
	v_mul_f32_e32 v42, v42, v230
	v_and_b32_e32 v228, 0xffff0000, v217
	v_mul_f32_e32 v228, 0xbfb8aa3b, v228
	v_exp_f32_e32 v229, v228
	s_nop 0
	v_add_f32_e32 v229, 1.0, v229
	s_nop 0
	v_div_scale_f32 v230, s[2:3], v229, v229, 1.0
	v_rcp_f32_e32 v231, v230
	s_nop 0
	v_fma_f32 v232, -v230, v231, 1.0
	v_fmac_f32_e32 v231, v232, v231
	v_div_scale_f32 v233, vcc, 1.0, v229, 1.0
	v_mul_f32_e32 v234, v233, v231
	v_fma_f32 v235, -v230, v234, v233
	v_fmac_f32_e32 v234, v235, v231
	v_fma_f32 v230, -v230, v234, v233
	v_div_fmas_f32 v230, v230, v231, v234
	v_div_fixup_f32 v230, v230, v229, 1.0
	v_mul_f32_e32 v43, v43, v230
	v_lshlrev_b32_e32 v228, 16, v218
	v_mul_f32_e32 v228, 0xbfb8aa3b, v228
	v_exp_f32_e32 v229, v228
	s_nop 0
	v_add_f32_e32 v229, 1.0, v229
	s_nop 0
	v_div_scale_f32 v230, s[2:3], v229, v229, 1.0
	v_rcp_f32_e32 v231, v230
	s_nop 0
	v_fma_f32 v232, -v230, v231, 1.0
	v_fmac_f32_e32 v231, v232, v231
	v_div_scale_f32 v233, vcc, 1.0, v229, 1.0
	v_mul_f32_e32 v234, v233, v231
	v_fma_f32 v235, -v230, v234, v233
	v_fmac_f32_e32 v234, v235, v231
	v_fma_f32 v230, -v230, v234, v233
	v_div_fmas_f32 v230, v230, v231, v234
	v_div_fixup_f32 v230, v230, v229, 1.0
	v_mul_f32_e32 v36, v36, v230
	v_and_b32_e32 v228, 0xffff0000, v218
	v_mul_f32_e32 v228, 0xbfb8aa3b, v228
	v_exp_f32_e32 v229, v228
	s_nop 0
	v_add_f32_e32 v229, 1.0, v229
	s_nop 0
	v_div_scale_f32 v230, s[2:3], v229, v229, 1.0
	v_rcp_f32_e32 v231, v230
	s_nop 0
	v_fma_f32 v232, -v230, v231, 1.0
	v_fmac_f32_e32 v231, v232, v231
	v_div_scale_f32 v233, vcc, 1.0, v229, 1.0
	v_mul_f32_e32 v234, v233, v231
	v_fma_f32 v235, -v230, v234, v233
	v_fmac_f32_e32 v234, v235, v231
	v_fma_f32 v230, -v230, v234, v233
	v_div_fmas_f32 v230, v230, v231, v234
	v_div_fixup_f32 v230, v230, v229, 1.0
	v_mul_f32_e32 v37, v37, v230
	v_lshlrev_b32_e32 v228, 16, v219
	v_mul_f32_e32 v228, 0xbfb8aa3b, v228
	v_exp_f32_e32 v229, v228
	s_nop 0
	v_add_f32_e32 v229, 1.0, v229
	s_nop 0
	v_div_scale_f32 v230, s[2:3], v229, v229, 1.0
	v_rcp_f32_e32 v231, v230
	s_nop 0
	v_fma_f32 v232, -v230, v231, 1.0
	v_fmac_f32_e32 v231, v232, v231
	v_div_scale_f32 v233, vcc, 1.0, v229, 1.0
	v_mul_f32_e32 v234, v233, v231
	v_fma_f32 v235, -v230, v234, v233
	v_fmac_f32_e32 v234, v235, v231
	v_fma_f32 v230, -v230, v234, v233
	v_div_fmas_f32 v230, v230, v231, v234
	v_div_fixup_f32 v230, v230, v229, 1.0
	v_mul_f32_e32 v38, v38, v230
	v_and_b32_e32 v228, 0xffff0000, v219
	v_mul_f32_e32 v228, 0xbfb8aa3b, v228
	v_exp_f32_e32 v229, v228
	s_nop 0
	v_add_f32_e32 v229, 1.0, v229
	s_nop 0
	v_div_scale_f32 v230, s[2:3], v229, v229, 1.0
	v_rcp_f32_e32 v231, v230
	s_nop 0
	v_fma_f32 v232, -v230, v231, 1.0
	v_fmac_f32_e32 v231, v232, v231
	v_div_scale_f32 v233, vcc, 1.0, v229, 1.0
	v_mul_f32_e32 v234, v233, v231
	v_fma_f32 v235, -v230, v234, v233
	v_fmac_f32_e32 v234, v235, v231
	v_fma_f32 v230, -v230, v234, v233
	v_div_fmas_f32 v230, v230, v231, v234
	v_div_fixup_f32 v230, v230, v229, 1.0
	v_mul_f32_e32 v39, v39, v230
	s_and_b64 vcc, exec, s[44:45]
	s_cbranch_vccz .Lmy_br_nopv_add_5_1
	v_lshlrev_b32_e32 v228, 16, v224
	v_add_f32_e32 v40, v40, v228
	v_and_b32_e32 v228, 0xffff0000, v224
	v_add_f32_e32 v41, v41, v228
	v_lshlrev_b32_e32 v228, 16, v225
	v_add_f32_e32 v42, v42, v228
	v_and_b32_e32 v228, 0xffff0000, v225
	v_add_f32_e32 v43, v43, v228
	v_lshlrev_b32_e32 v228, 16, v226
	v_add_f32_e32 v36, v36, v228
	v_and_b32_e32 v228, 0xffff0000, v226
	v_add_f32_e32 v37, v37, v228
	v_lshlrev_b32_e32 v228, 16, v227
	v_add_f32_e32 v38, v38, v228
	v_and_b32_e32 v228, 0xffff0000, v227
	v_add_f32_e32 v39, v39, v228
; __device__ __forceinline__ float b2f(u16 b) { return __uint_as_float(((uint32_t)b) << 16); }
; __device__ __forceinline__ float sigmoidf_(float x) { return 1.0f / (1.0f + __expf(-x)); }
; __device__ __forceinline__ void gemm_phase(const Ctx& cx, const GemmArgs& g_, char* shm) {
;     ...
;               const uint2 gv = *(const uint2*)(g.gate + (size_t)tok * NP + n0);
;               float v0 = sigmoidf_(b2f((u16)(gv.x & 0xffff))) * a[0], v1 = sigmoidf_(b2f((u16)(gv.x >> 16))) * a[1];
;               float v2 = sigmoidf_(b2f((u16)(gv.y & 0xffff))) * a[2], v3 = sigmoidf_(b2f((u16)(gv.y >> 16))) * a[3];
;               uint2* mp = (uint2*)(g.outb + (size_t)tok * DM + n0);
;               if (g.epi != EPI_BR0) {
;                 const uint2 pv = *mp;
;                 v0 += b2f((u16)(pv.x & 0xffff)); v1 += b2f((u16)(pv.x >> 16));
;                 v2 += b2f((u16)(pv.y & 0xffff)); v3 += b2f((u16)(pv.y >> 16));
;               }
;               uint2 o; o.x = pack2(v0, v1); o.y = pack2(v2, v3);
;               *mp = o;
.Lmy_br_nopv_add_5_1:
	v_cvt_pk_bf16_f32 v240, v40, v41
	v_cvt_pk_bf16_f32 v241, v42, v43
	v_cvt_pk_bf16_f32 v242, v36, v37
	v_cvt_pk_bf16_f32 v243, v38, v39
	s_nop 1
	v_permlane16_swap_b32_e32 v240, v242
	v_permlane16_swap_b32_e32 v241, v243
	v_mov_b32_e32 v244, v240
	v_mov_b32_e32 v245, v241
	v_mov_b32_e32 v246, v242
	v_mov_b32_e32 v247, v243
	v_mov_b32_dpp v240, v236 row_ror:8 row_mask:0xf bank_mask:0x3
	v_mov_b32_dpp v241, v237 row_ror:8 row_mask:0xf bank_mask:0x3
	v_mov_b32_dpp v242, v238 row_ror:8 row_mask:0xf bank_mask:0x3
	v_mov_b32_dpp v243, v239 row_ror:8 row_mask:0xf bank_mask:0x3
	v_mov_b32_dpp v236, v244 row_ror:8 row_mask:0xf bank_mask:0xc
	v_mov_b32_dpp v237, v245 row_ror:8 row_mask:0xf bank_mask:0xc
	v_mov_b32_dpp v238, v246 row_ror:8 row_mask:0xf bank_mask:0xc
	v_mov_b32_dpp v239, v247 row_ror:8 row_mask:0xf bank_mask:0xc
	global_store_dwordx4 v[188:189], v[236:239], off offset:288
	global_store_dwordx4 v[190:191], v[240:243], off offset:288
	s_nop 1
	v_lshl_add_u64 v[188:189], v[184:185], 0, s[10:11]
	v_lshl_add_u64 v[188:189], v[188:189], 0, s[8:9]
	v_lshl_add_u64 v[190:191], v[188:189], 0, s[6:7]
	v_add_u32_e32 v195, 144, v194
	v_mov_b64_e32 v[244:245], s[22:23]
	v_mad_i64_i32 v[244:245], s[4:5], v195, s76, v[244:245]
	v_lshl_add_u64 v[244:245], v[186:187], 1, v[244:245]
	global_load_dwordx2 v[212:213], v[244:245], off offset:256
	global_load_dwordx2 v[214:215], v[244:245], off offset:288
	global_load_dwordx2 v[216:217], v[244:245], off offset:320
	global_load_dwordx2 v[218:219], v[244:245], off offset:352
	s_and_b64 vcc, exec, s[44:45]
	s_cbranch_vccz .Lmy_br_nopv_ld_7
	v_mov_b32_e32 v192, v195
	v_ashrrev_i32_e32 v193, 31, v195
	v_lshlrev_b64 v[192:193], 12, v[192:193]
	v_lshl_add_u64 v[192:193], s[20:21], 0, v[192:193]
	v_lshl_add_u64 v[192:193], v[186:187], 1, v[192:193]
	global_load_dwordx2 v[220:221], v[192:193], off offset:256
	global_load_dwordx2 v[222:223], v[192:193], off offset:288
	global_load_dwordx2 v[224:225], v[192:193], off offset:320
	global_load_dwordx2 v[226:227], v[192:193], off offset:352

; __device__ __forceinline__ float b2f(u16 b) { return __uint_as_float(((uint32_t)b) << 16); }
; __device__ __forceinline__ float sigmoidf_(float x) { return 1.0f / (1.0f + __expf(-x)); }
; __device__ __forceinline__ void gemm_phase(const Ctx& cx, const GemmArgs& g_, char* shm) {
;     ...
;               const uint2 gv = *(const uint2*)(g.gate + (size_t)tok * NP + n0);
;               float v0 = sigmoidf_(b2f((u16)(gv.x & 0xffff))) * a[0], v1 = sigmoidf_(b2f((u16)(gv.x >> 16))) * a[1];
;               float v2 = sigmoidf_(b2f((u16)(gv.y & 0xffff))) * a[2], v3 = sigmoidf_(b2f((u16)(gv.y >> 16))) * a[3];
;               uint2* mp = (uint2*)(g.outb + (size_t)tok * DM + n0);
;               if (g.epi != EPI_BR0) {
;                 const uint2 pv = *mp;
;                 v0 += b2f((u16)(pv.x & 0xffff)); v1 += b2f((u16)(pv.x >> 16));
;                 v2 += b2f((u16)(pv.y & 0xffff)); v3 += b2f((u16)(pv.y >> 16));
;               }
;               uint2 o; o.x = pack2(v0, v1); o.y = pack2(v2, v3);
;               *mp = o;
.Lmy_br_wj_6:
	v_lshlrev_b32_e32 v228, 16, v196
	v_mul_f32_e32 v228, 0xbfb8aa3b, v228
	v_exp_f32_e32 v229, v228
	s_nop 0
	v_add_f32_e32 v229, 1.0, v229
	s_nop 0
	v_div_scale_f32 v230, s[2:3], v229, v229, 1.0
	v_rcp_f32_e32 v231, v230
	s_nop 0
	v_fma_f32 v232, -v230, v231, 1.0
	v_fmac_f32_e32 v231, v232, v231
	v_div_scale_f32 v233, vcc, 1.0, v229, 1.0
	v_mul_f32_e32 v234, v233, v231
	v_fma_f32 v235, -v230, v234, v233
	v_fmac_f32_e32 v234, v235, v231
	v_fma_f32 v230, -v230, v234, v233
	v_div_fmas_f32 v230, v230, v231, v234
	v_div_fixup_f32 v230, v230, v229, 1.0
	v_mul_f32_e32 v32, v32, v230
	v_and_b32_e32 v228, 0xffff0000, v196
	v_mul_f32_e32 v228, 0xbfb8aa3b, v228
	v_exp_f32_e32 v229, v228
	s_nop 0
	v_add_f32_e32 v229, 1.0, v229
	s_nop 0
	v_div_scale_f32 v230, s[2:3], v229, v229, 1.0
	v_rcp_f32_e32 v231, v230
	s_nop 0
	v_fma_f32 v232, -v230, v231, 1.0
	v_fmac_f32_e32 v231, v232, v231
	v_div_scale_f32 v233, vcc, 1.0, v229, 1.0
	v_mul_f32_e32 v234, v233, v231
	v_fma_f32 v235, -v230, v234, v233
	v_fmac_f32_e32 v234, v235, v231
	v_fma_f32 v230, -v230, v234, v233
	v_div_fmas_f32 v230, v230, v231, v234
	v_div_fixup_f32 v230, v230, v229, 1.0
	v_mul_f32_e32 v33, v33, v230
	v_lshlrev_b32_e32 v228, 16, v197
	v_mul_f32_e32 v228, 0xbfb8aa3b, v228
	v_exp_f32_e32 v229, v228
	s_nop 0
	v_add_f32_e32 v229, 1.0, v229
	s_nop 0
	v_div_scale_f32 v230, s[2:3], v229, v229, 1.0
	v_rcp_f32_e32 v231, v230
	s_nop 0
	v_fma_f32 v232, -v230, v231, 1.0
	v_fmac_f32_e32 v231, v232, v231
	v_div_scale_f32 v233, vcc, 1.0, v229, 1.0
	v_mul_f32_e32 v234, v233, v231
	v_fma_f32 v235, -v230, v234, v233
	v_fmac_f32_e32 v234, v235, v231
	v_fma_f32 v230, -v230, v234, v233
	v_div_fmas_f32 v230, v230, v231, v234
	v_div_fixup_f32 v230, v230, v229, 1.0
	v_mul_f32_e32 v34, v34, v230
	v_and_b32_e32 v228, 0xffff0000, v197
	v_mul_f32_e32 v228, 0xbfb8aa3b, v228
	v_exp_f32_e32 v229, v228
	s_nop 0
	v_add_f32_e32 v229, 1.0, v229
	s_nop 0
	v_div_scale_f32 v230, s[2:3], v229, v229, 1.0
	v_rcp_f32_e32 v231, v230
	s_nop 0
	v_fma_f32 v232, -v230, v231, 1.0
	v_fmac_f32_e32 v231, v232, v231
	v_div_scale_f32 v233, vcc, 1.0, v229, 1.0
	v_mul_f32_e32 v234, v233, v231
	v_fma_f32 v235, -v230, v234, v233
	v_fmac_f32_e32 v234, v235, v231
	v_fma_f32 v230, -v230, v234, v233
	v_div_fmas_f32 v230, v230, v231, v234
	v_div_fixup_f32 v230, v230, v229, 1.0
	v_mul_f32_e32 v35, v35, v230
	v_lshlrev_b32_e32 v228, 16, v198
	v_mul_f32_e32 v228, 0xbfb8aa3b, v228
	v_exp_f32_e32 v229, v228
	s_nop 0
	v_add_f32_e32 v229, 1.0, v229
	s_nop 0
	v_div_scale_f32 v230, s[2:3], v229, v229, 1.0
	v_rcp_f32_e32 v231, v230
	s_nop 0
	v_fma_f32 v232, -v230, v231, 1.0
	v_fmac_f32_e32 v231, v232, v231
	v_div_scale_f32 v233, vcc, 1.0, v229, 1.0
	v_mul_f32_e32 v234, v233, v231
	v_fma_f32 v235, -v230, v234, v233
	v_fmac_f32_e32 v234, v235, v231
	v_fma_f32 v230, -v230, v234, v233
	v_div_fmas_f32 v230, v230, v231, v234
	v_div_fixup_f32 v230, v230, v229, 1.0
	v_mul_f32_e32 v28, v28, v230
	v_and_b32_e32 v228, 0xffff0000, v198
	v_mul_f32_e32 v228, 0xbfb8aa3b, v228
	v_exp_f32_e32 v229, v228
	s_nop 0
	v_add_f32_e32 v229, 1.0, v229
	s_nop 0
	v_div_scale_f32 v230, s[2:3], v229, v229, 1.0
	v_rcp_f32_e32 v231, v230
	s_nop 0
	v_fma_f32 v232, -v230, v231, 1.0
	v_fmac_f32_e32 v231, v232, v231
	v_div_scale_f32 v233, vcc, 1.0, v229, 1.0
	v_mul_f32_e32 v234, v233, v231
	v_fma_f32 v235, -v230, v234, v233
	v_fmac_f32_e32 v234, v235, v231
	v_fma_f32 v230, -v230, v234, v233
	v_div_fmas_f32 v230, v230, v231, v234
	v_div_fixup_f32 v230, v230, v229, 1.0
	v_mul_f32_e32 v29, v29, v230
	v_lshlrev_b32_e32 v228, 16, v199
	v_mul_f32_e32 v228, 0xbfb8aa3b, v228
	v_exp_f32_e32 v229, v228
	s_nop 0
	v_add_f32_e32 v229, 1.0, v229
	s_nop 0
	v_div_scale_f32 v230, s[2:3], v229, v229, 1.0
	v_rcp_f32_e32 v231, v230
	s_nop 0
	v_fma_f32 v232, -v230, v231, 1.0
	v_fmac_f32_e32 v231, v232, v231
	v_div_scale_f32 v233, vcc, 1.0, v229, 1.0
	v_mul_f32_e32 v234, v233, v231
	v_fma_f32 v235, -v230, v234, v233
	v_fmac_f32_e32 v234, v235, v231
	v_fma_f32 v230, -v230, v234, v233
	v_div_fmas_f32 v230, v230, v231, v234
	v_div_fixup_f32 v230, v230, v229, 1.0
	v_mul_f32_e32 v30, v30, v230
	v_and_b32_e32 v228, 0xffff0000, v199
	v_mul_f32_e32 v228, 0xbfb8aa3b, v228
	v_exp_f32_e32 v229, v228
	s_nop 0
	v_add_f32_e32 v229, 1.0, v229
	s_nop 0
	v_div_scale_f32 v230, s[2:3], v229, v229, 1.0
	v_rcp_f32_e32 v231, v230
	s_nop 0
	v_fma_f32 v232, -v230, v231, 1.0
	v_fmac_f32_e32 v231, v232, v231
	v_div_scale_f32 v233, vcc, 1.0, v229, 1.0
	v_mul_f32_e32 v234, v233, v231
	v_fma_f32 v235, -v230, v234, v233
	v_fmac_f32_e32 v234, v235, v231
	v_fma_f32 v230, -v230, v234, v233
	v_div_fmas_f32 v230, v230, v231, v234
	v_div_fixup_f32 v230, v230, v229, 1.0
	v_mul_f32_e32 v31, v31, v230
	s_and_b64 vcc, exec, s[44:45]
	s_cbranch_vccz .Lmy_br_nopv_add_6_0
	v_lshlrev_b32_e32 v228, 16, v204
	v_add_f32_e32 v32, v32, v228
	v_and_b32_e32 v228, 0xffff0000, v204
	v_add_f32_e32 v33, v33, v228
	v_lshlrev_b32_e32 v228, 16, v205
	v_add_f32_e32 v34, v34, v228
	v_and_b32_e32 v228, 0xffff0000, v205
	v_add_f32_e32 v35, v35, v228
	v_lshlrev_b32_e32 v228, 16, v206
	v_add_f32_e32 v28, v28, v228
	v_and_b32_e32 v228, 0xffff0000, v206
	v_add_f32_e32 v29, v29, v228
	v_lshlrev_b32_e32 v228, 16, v207
	v_add_f32_e32 v30, v30, v228
	v_and_b32_e32 v228, 0xffff0000, v207
	v_add_f32_e32 v31, v31, v228
; __device__ __forceinline__ float b2f(u16 b) { return __uint_as_float(((uint32_t)b) << 16); }
; __device__ __forceinline__ float sigmoidf_(float x) { return 1.0f / (1.0f + __expf(-x)); }
; __device__ __forceinline__ void gemm_phase(const Ctx& cx, const GemmArgs& g_, char* shm) {
;     ...
;               const uint2 gv = *(const uint2*)(g.gate + (size_t)tok * NP + n0);
;               float v0 = sigmoidf_(b2f((u16)(gv.x & 0xffff))) * a[0], v1 = sigmoidf_(b2f((u16)(gv.x >> 16))) * a[1];
;               float v2 = sigmoidf_(b2f((u16)(gv.y & 0xffff))) * a[2], v3 = sigmoidf_(b2f((u16)(gv.y >> 16))) * a[3];
;               uint2* mp = (uint2*)(g.outb + (size_t)tok * DM + n0);
;               if (g.epi != EPI_BR0) {
;                 const uint2 pv = *mp;
;                 v0 += b2f((u16)(pv.x & 0xffff)); v1 += b2f((u16)(pv.x >> 16));
;                 v2 += b2f((u16)(pv.y & 0xffff)); v3 += b2f((u16)(pv.y >> 16));
;               }
;               uint2 o; o.x = pack2(v0, v1); o.y = pack2(v2, v3);
;               *mp = o;
.Lmy_br_nopv_add_6_0:
	v_cvt_pk_bf16_f32 v236, v32, v33
	v_cvt_pk_bf16_f32 v237, v34, v35
	v_cvt_pk_bf16_f32 v238, v28, v29
	v_cvt_pk_bf16_f32 v239, v30, v31
	s_nop 1
	v_permlane16_swap_b32_e32 v236, v238
	v_permlane16_swap_b32_e32 v237, v239
	v_lshlrev_b32_e32 v228, 16, v200
	v_mul_f32_e32 v228, 0xbfb8aa3b, v228
	v_exp_f32_e32 v229, v228
	s_nop 0
	v_add_f32_e32 v229, 1.0, v229
	s_nop 0
	v_div_scale_f32 v230, s[2:3], v229, v229, 1.0
	v_rcp_f32_e32 v231, v230
	s_nop 0
	v_fma_f32 v232, -v230, v231, 1.0
	v_fmac_f32_e32 v231, v232, v231
	v_div_scale_f32 v233, vcc, 1.0, v229, 1.0
	v_mul_f32_e32 v234, v233, v231
	v_fma_f32 v235, -v230, v234, v233
	v_fmac_f32_e32 v234, v235, v231
	v_fma_f32 v230, -v230, v234, v233
	v_div_fmas_f32 v230, v230, v231, v234
	v_div_fixup_f32 v230, v230, v229, 1.0
	v_mul_f32_e32 v24, v24, v230
	v_and_b32_e32 v228, 0xffff0000, v200
	v_mul_f32_e32 v228, 0xbfb8aa3b, v228
	v_exp_f32_e32 v229, v228
	s_nop 0
	v_add_f32_e32 v229, 1.0, v229
	s_nop 0
	v_div_scale_f32 v230, s[2:3], v229, v229, 1.0
	v_rcp_f32_e32 v231, v230
	s_nop 0
	v_fma_f32 v232, -v230, v231, 1.0
	v_fmac_f32_e32 v231, v232, v231
	v_div_scale_f32 v233, vcc, 1.0, v229, 1.0
	v_mul_f32_e32 v234, v233, v231
	v_fma_f32 v235, -v230, v234, v233
	v_fmac_f32_e32 v234, v235, v231
	v_fma_f32 v230, -v230, v234, v233
	v_div_fmas_f32 v230, v230, v231, v234
	v_div_fixup_f32 v230, v230, v229, 1.0
	v_mul_f32_e32 v25, v25, v230
	v_lshlrev_b32_e32 v228, 16, v201
	v_mul_f32_e32 v228, 0xbfb8aa3b, v228
	v_exp_f32_e32 v229, v228
	s_nop 0
	v_add_f32_e32 v229, 1.0, v229
	s_nop 0
	v_div_scale_f32 v230, s[2:3], v229, v229, 1.0
	v_rcp_f32_e32 v231, v230
	s_nop 0
	v_fma_f32 v232, -v230, v231, 1.0
	v_fmac_f32_e32 v231, v232, v231
	v_div_scale_f32 v233, vcc, 1.0, v229, 1.0
	v_mul_f32_e32 v234, v233, v231
	v_fma_f32 v235, -v230, v234, v233
	v_fmac_f32_e32 v234, v235, v231
	v_fma_f32 v230, -v230, v234, v233
	v_div_fmas_f32 v230, v230, v231, v234
	v_div_fixup_f32 v230, v230, v229, 1.0
	v_mul_f32_e32 v26, v26, v230
	v_and_b32_e32 v228, 0xffff0000, v201
	v_mul_f32_e32 v228, 0xbfb8aa3b, v228
	v_exp_f32_e32 v229, v228
	s_nop 0
	v_add_f32_e32 v229, 1.0, v229
	s_nop 0
	v_div_scale_f32 v230, s[2:3], v229, v229, 1.0
	v_rcp_f32_e32 v231, v230
	s_nop 0
	v_fma_f32 v232, -v230, v231, 1.0
	v_fmac_f32_e32 v231, v232, v231
	v_div_scale_f32 v233, vcc, 1.0, v229, 1.0
	v_mul_f32_e32 v234, v233, v231
	v_fma_f32 v235, -v230, v234, v233
	v_fmac_f32_e32 v234, v235, v231
	v_fma_f32 v230, -v230, v234, v233
	v_div_fmas_f32 v230, v230, v231, v234
	v_div_fixup_f32 v230, v230, v229, 1.0
	v_mul_f32_e32 v27, v27, v230
	v_lshlrev_b32_e32 v228, 16, v202
	v_mul_f32_e32 v228, 0xbfb8aa3b, v228
	v_exp_f32_e32 v229, v228
	s_nop 0
	v_add_f32_e32 v229, 1.0, v229
	s_nop 0
	v_div_scale_f32 v230, s[2:3], v229, v229, 1.0
	v_rcp_f32_e32 v231, v230
	s_nop 0
	v_fma_f32 v232, -v230, v231, 1.0
	v_fmac_f32_e32 v231, v232, v231
	v_div_scale_f32 v233, vcc, 1.0, v229, 1.0
	v_mul_f32_e32 v234, v233, v231
	v_fma_f32 v235, -v230, v234, v233
	v_fmac_f32_e32 v234, v235, v231
	v_fma_f32 v230, -v230, v234, v233
	v_div_fmas_f32 v230, v230, v231, v234
	v_div_fixup_f32 v230, v230, v229, 1.0
	v_mul_f32_e32 v20, v20, v230
	v_and_b32_e32 v228, 0xffff0000, v202
	v_mul_f32_e32 v228, 0xbfb8aa3b, v228
	v_exp_f32_e32 v229, v228
	s_nop 0
	v_add_f32_e32 v229, 1.0, v229
	s_nop 0
	v_div_scale_f32 v230, s[2:3], v229, v229, 1.0
	v_rcp_f32_e32 v231, v230
	s_nop 0
	v_fma_f32 v232, -v230, v231, 1.0
	v_fmac_f32_e32 v231, v232, v231
	v_div_scale_f32 v233, vcc, 1.0, v229, 1.0
	v_mul_f32_e32 v234, v233, v231
	v_fma_f32 v235, -v230, v234, v233
	v_fmac_f32_e32 v234, v235, v231
	v_fma_f32 v230, -v230, v234, v233
	v_div_fmas_f32 v230, v230, v231, v234
	v_div_fixup_f32 v230, v230, v229, 1.0
	v_mul_f32_e32 v21, v21, v230
	v_lshlrev_b32_e32 v228, 16, v203
	v_mul_f32_e32 v228, 0xbfb8aa3b, v228
	v_exp_f32_e32 v229, v228
	s_nop 0
	v_add_f32_e32 v229, 1.0, v229
	s_nop 0
	v_div_scale_f32 v230, s[2:3], v229, v229, 1.0
	v_rcp_f32_e32 v231, v230
	s_nop 0
	v_fma_f32 v232, -v230, v231, 1.0
	v_fmac_f32_e32 v231, v232, v231
	v_div_scale_f32 v233, vcc, 1.0, v229, 1.0
	v_mul_f32_e32 v234, v233, v231
	v_fma_f32 v235, -v230, v234, v233
	v_fmac_f32_e32 v234, v235, v231
	v_fma_f32 v230, -v230, v234, v233
	v_div_fmas_f32 v230, v230, v231, v234
	v_div_fixup_f32 v230, v230, v229, 1.0
	v_mul_f32_e32 v22, v22, v230
	v_and_b32_e32 v228, 0xffff0000, v203
	v_mul_f32_e32 v228, 0xbfb8aa3b, v228
	v_exp_f32_e32 v229, v228
	s_nop 0
	v_add_f32_e32 v229, 1.0, v229
	s_nop 0
	v_div_scale_f32 v230, s[2:3], v229, v229, 1.0
	v_rcp_f32_e32 v231, v230
	s_nop 0
	v_fma_f32 v232, -v230, v231, 1.0
	v_fmac_f32_e32 v231, v232, v231
	v_div_scale_f32 v233, vcc, 1.0, v229, 1.0
	v_mul_f32_e32 v234, v233, v231
	v_fma_f32 v235, -v230, v234, v233
	v_fmac_f32_e32 v234, v235, v231
	v_fma_f32 v230, -v230, v234, v233
	v_div_fmas_f32 v230, v230, v231, v234
	v_div_fixup_f32 v230, v230, v229, 1.0
	v_mul_f32_e32 v23, v23, v230
	s_and_b64 vcc, exec, s[44:45]
	s_cbranch_vccz .Lmy_br_nopv_add_6_1
	v_lshlrev_b32_e32 v228, 16, v208
	v_add_f32_e32 v24, v24, v228
	v_and_b32_e32 v228, 0xffff0000, v208
	v_add_f32_e32 v25, v25, v228
	v_lshlrev_b32_e32 v228, 16, v209
	v_add_f32_e32 v26, v26, v228
	v_and_b32_e32 v228, 0xffff0000, v209
	v_add_f32_e32 v27, v27, v228
	v_lshlrev_b32_e32 v228, 16, v210
	v_add_f32_e32 v20, v20, v228
	v_and_b32_e32 v228, 0xffff0000, v210
	v_add_f32_e32 v21, v21, v228
	v_lshlrev_b32_e32 v228, 16, v211
	v_add_f32_e32 v22, v22, v228
	v_and_b32_e32 v228, 0xffff0000, v211
	v_add_f32_e32 v23, v23, v228
; __device__ __forceinline__ float b2f(u16 b) { return __uint_as_float(((uint32_t)b) << 16); }
; __device__ __forceinline__ float sigmoidf_(float x) { return 1.0f / (1.0f + __expf(-x)); }
; __device__ __forceinline__ void gemm_phase(const Ctx& cx, const GemmArgs& g_, char* shm) {
;     ...
;               const uint2 gv = *(const uint2*)(g.gate + (size_t)tok * NP + n0);
;               float v0 = sigmoidf_(b2f((u16)(gv.x & 0xffff))) * a[0], v1 = sigmoidf_(b2f((u16)(gv.x >> 16))) * a[1];
;               float v2 = sigmoidf_(b2f((u16)(gv.y & 0xffff))) * a[2], v3 = sigmoidf_(b2f((u16)(gv.y >> 16))) * a[3];
;               uint2* mp = (uint2*)(g.outb + (size_t)tok * DM + n0);
;               if (g.epi != EPI_BR0) {
;                 const uint2 pv = *mp;
;                 v0 += b2f((u16)(pv.x & 0xffff)); v1 += b2f((u16)(pv.x >> 16));
;                 v2 += b2f((u16)(pv.y & 0xffff)); v3 += b2f((u16)(pv.y >> 16));
;               }
;               uint2 o; o.x = pack2(v0, v1); o.y = pack2(v2, v3);
;               *mp = o;
.Lmy_br_nopv_add_6_1:
	v_cvt_pk_bf16_f32 v240, v24, v25
	v_cvt_pk_bf16_f32 v241, v26, v27
	v_cvt_pk_bf16_f32 v242, v20, v21
	v_cvt_pk_bf16_f32 v243, v22, v23
	s_nop 1
	v_permlane16_swap_b32_e32 v240, v242
	v_permlane16_swap_b32_e32 v241, v243
	v_mov_b32_e32 v244, v240
	v_mov_b32_e32 v245, v241
	v_mov_b32_e32 v246, v242
	v_mov_b32_e32 v247, v243
	v_mov_b32_dpp v240, v236 row_ror:8 row_mask:0xf bank_mask:0x3
	v_mov_b32_dpp v241, v237 row_ror:8 row_mask:0xf bank_mask:0x3
	v_mov_b32_dpp v242, v238 row_ror:8 row_mask:0xf bank_mask:0x3
	v_mov_b32_dpp v243, v239 row_ror:8 row_mask:0xf bank_mask:0x3
	v_mov_b32_dpp v236, v244 row_ror:8 row_mask:0xf bank_mask:0xc
	v_mov_b32_dpp v237, v245 row_ror:8 row_mask:0xf bank_mask:0xc
	v_mov_b32_dpp v238, v246 row_ror:8 row_mask:0xf bank_mask:0xc
	v_mov_b32_dpp v239, v247 row_ror:8 row_mask:0xf bank_mask:0xc
	global_store_dwordx4 v[188:189], v[236:239], off offset:32
	global_store_dwordx4 v[190:191], v[240:243], off offset:32
	s_nop 1
	s_and_b64 vcc, exec, s[44:45]
	s_cbranch_vccz .Lmy_br_w0_7
	s_waitcnt vmcnt(2)
	s_branch .Lmy_br_wj_7
.Lmy_br_w0_7:
	s_waitcnt vmcnt(2)
.Lmy_br_wj_7:
	v_lshlrev_b32_e32 v228, 16, v212
	v_mul_f32_e32 v228, 0xbfb8aa3b, v228
	v_exp_f32_e32 v229, v228
	s_nop 0
	v_add_f32_e32 v229, 1.0, v229
	s_nop 0
	v_div_scale_f32 v230, s[2:3], v229, v229, 1.0
	v_rcp_f32_e32 v231, v230
	s_nop 0
	v_fma_f32 v232, -v230, v231, 1.0
	v_fmac_f32_e32 v231, v232, v231
	v_div_scale_f32 v233, vcc, 1.0, v229, 1.0
	v_mul_f32_e32 v234, v233, v231
	v_fma_f32 v235, -v230, v234, v233
	v_fmac_f32_e32 v234, v235, v231
	v_fma_f32 v230, -v230, v234, v233
	v_div_fmas_f32 v230, v230, v231, v234
	v_div_fixup_f32 v230, v230, v229, 1.0
	v_mul_f32_e32 v16, v16, v230
	v_and_b32_e32 v228, 0xffff0000, v212
	v_mul_f32_e32 v228, 0xbfb8aa3b, v228
	v_exp_f32_e32 v229, v228
	s_nop 0
	v_add_f32_e32 v229, 1.0, v229
	s_nop 0
	v_div_scale_f32 v230, s[2:3], v229, v229, 1.0
	v_rcp_f32_e32 v231, v230
	s_nop 0
	v_fma_f32 v232, -v230, v231, 1.0
	v_fmac_f32_e32 v231, v232, v231
	v_div_scale_f32 v233, vcc, 1.0, v229, 1.0
	v_mul_f32_e32 v234, v233, v231
	v_fma_f32 v235, -v230, v234, v233
	v_fmac_f32_e32 v234, v235, v231
	v_fma_f32 v230, -v230, v234, v233
	v_div_fmas_f32 v230, v230, v231, v234
	v_div_fixup_f32 v230, v230, v229, 1.0
	v_mul_f32_e32 v17, v17, v230
	v_lshlrev_b32_e32 v228, 16, v213
	v_mul_f32_e32 v228, 0xbfb8aa3b, v228
	v_exp_f32_e32 v229, v228
	s_nop 0
	v_add_f32_e32 v229, 1.0, v229
	s_nop 0
	v_div_scale_f32 v230, s[2:3], v229, v229, 1.0
	v_rcp_f32_e32 v231, v230
	s_nop 0
	v_fma_f32 v232, -v230, v231, 1.0
	v_fmac_f32_e32 v231, v232, v231
	v_div_scale_f32 v233, vcc, 1.0, v229, 1.0
	v_mul_f32_e32 v234, v233, v231
	v_fma_f32 v235, -v230, v234, v233
	v_fmac_f32_e32 v234, v235, v231
	v_fma_f32 v230, -v230, v234, v233
	v_div_fmas_f32 v230, v230, v231, v234
	v_div_fixup_f32 v230, v230, v229, 1.0
	v_mul_f32_e32 v18, v18, v230
	v_and_b32_e32 v228, 0xffff0000, v213
	v_mul_f32_e32 v228, 0xbfb8aa3b, v228
	v_exp_f32_e32 v229, v228
	s_nop 0
	v_add_f32_e32 v229, 1.0, v229
	s_nop 0
	v_div_scale_f32 v230, s[2:3], v229, v229, 1.0
	v_rcp_f32_e32 v231, v230
	s_nop 0
	v_fma_f32 v232, -v230, v231, 1.0
	v_fmac_f32_e32 v231, v232, v231
	v_div_scale_f32 v233, vcc, 1.0, v229, 1.0
	v_mul_f32_e32 v234, v233, v231
	v_fma_f32 v235, -v230, v234, v233
	v_fmac_f32_e32 v234, v235, v231
	v_fma_f32 v230, -v230, v234, v233
	v_div_fmas_f32 v230, v230, v231, v234
	v_div_fixup_f32 v230, v230, v229, 1.0
	v_mul_f32_e32 v19, v19, v230
	v_lshlrev_b32_e32 v228, 16, v214
	v_mul_f32_e32 v228, 0xbfb8aa3b, v228
	v_exp_f32_e32 v229, v228
	s_nop 0
	v_add_f32_e32 v229, 1.0, v229
	s_nop 0
	v_div_scale_f32 v230, s[2:3], v229, v229, 1.0
	v_rcp_f32_e32 v231, v230
	s_nop 0
	v_fma_f32 v232, -v230, v231, 1.0
	v_fmac_f32_e32 v231, v232, v231
	v_div_scale_f32 v233, vcc, 1.0, v229, 1.0
	v_mul_f32_e32 v234, v233, v231
	v_fma_f32 v235, -v230, v234, v233
	v_fmac_f32_e32 v234, v235, v231
	v_fma_f32 v230, -v230, v234, v233
	v_div_fmas_f32 v230, v230, v231, v234
	v_div_fixup_f32 v230, v230, v229, 1.0
	v_mul_f32_e32 v12, v12, v230
	v_and_b32_e32 v228, 0xffff0000, v214
	v_mul_f32_e32 v228, 0xbfb8aa3b, v228
	v_exp_f32_e32 v229, v228
	s_nop 0
	v_add_f32_e32 v229, 1.0, v229
	s_nop 0
	v_div_scale_f32 v230, s[2:3], v229, v229, 1.0
	v_rcp_f32_e32 v231, v230
	s_nop 0
	v_fma_f32 v232, -v230, v231, 1.0
	v_fmac_f32_e32 v231, v232, v231
	v_div_scale_f32 v233, vcc, 1.0, v229, 1.0
	v_mul_f32_e32 v234, v233, v231
	v_fma_f32 v235, -v230, v234, v233
	v_fmac_f32_e32 v234, v235, v231
	v_fma_f32 v230, -v230, v234, v233
	v_div_fmas_f32 v230, v230, v231, v234
	v_div_fixup_f32 v230, v230, v229, 1.0
	v_mul_f32_e32 v13, v13, v230
	v_lshlrev_b32_e32 v228, 16, v215
	v_mul_f32_e32 v228, 0xbfb8aa3b, v228
	v_exp_f32_e32 v229, v228
	s_nop 0
	v_add_f32_e32 v229, 1.0, v229
	s_nop 0
	v_div_scale_f32 v230, s[2:3], v229, v229, 1.0
	v_rcp_f32_e32 v231, v230
	s_nop 0
	v_fma_f32 v232, -v230, v231, 1.0
	v_fmac_f32_e32 v231, v232, v231
	v_div_scale_f32 v233, vcc, 1.0, v229, 1.0
	v_mul_f32_e32 v234, v233, v231
	v_fma_f32 v235, -v230, v234, v233
	v_fmac_f32_e32 v234, v235, v231
	v_fma_f32 v230, -v230, v234, v233
	v_div_fmas_f32 v230, v230, v231, v234
	v_div_fixup_f32 v230, v230, v229, 1.0
	v_mul_f32_e32 v14, v14, v230
	v_and_b32_e32 v228, 0xffff0000, v215
	v_mul_f32_e32 v228, 0xbfb8aa3b, v228
	v_exp_f32_e32 v229, v228
	s_nop 0
	v_add_f32_e32 v229, 1.0, v229
	s_nop 0
	v_div_scale_f32 v230, s[2:3], v229, v229, 1.0
	v_rcp_f32_e32 v231, v230
	s_nop 0
	v_fma_f32 v232, -v230, v231, 1.0
	v_fmac_f32_e32 v231, v232, v231
	v_div_scale_f32 v233, vcc, 1.0, v229, 1.0
	v_mul_f32_e32 v234, v233, v231
	v_fma_f32 v235, -v230, v234, v233
	v_fmac_f32_e32 v234, v235, v231
	v_fma_f32 v230, -v230, v234, v233
	v_div_fmas_f32 v230, v230, v231, v234
	v_div_fixup_f32 v230, v230, v229, 1.0
	v_mul_f32_e32 v15, v15, v230
	s_and_b64 vcc, exec, s[44:45]
	s_cbranch_vccz .Lmy_br_nopv_add_7_0
	v_lshlrev_b32_e32 v228, 16, v220
	v_add_f32_e32 v16, v16, v228
	v_and_b32_e32 v228, 0xffff0000, v220
	v_add_f32_e32 v17, v17, v228
	v_lshlrev_b32_e32 v228, 16, v221
	v_add_f32_e32 v18, v18, v228
	v_and_b32_e32 v228, 0xffff0000, v221
	v_add_f32_e32 v19, v19, v228
	v_lshlrev_b32_e32 v228, 16, v222
	v_add_f32_e32 v12, v12, v228
	v_and_b32_e32 v228, 0xffff0000, v222
	v_add_f32_e32 v13, v13, v228
	v_lshlrev_b32_e32 v228, 16, v223
	v_add_f32_e32 v14, v14, v228
	v_and_b32_e32 v228, 0xffff0000, v223
	v_add_f32_e32 v15, v15, v228
; __device__ __forceinline__ float b2f(u16 b) { return __uint_as_float(((uint32_t)b) << 16); }
; __device__ __forceinline__ float sigmoidf_(float x) { return 1.0f / (1.0f + __expf(-x)); }
; __device__ __forceinline__ void gemm_phase(const Ctx& cx, const GemmArgs& g_, char* shm) {
;     ...
;               const uint2 gv = *(const uint2*)(g.gate + (size_t)tok * NP + n0);
;               float v0 = sigmoidf_(b2f((u16)(gv.x & 0xffff))) * a[0], v1 = sigmoidf_(b2f((u16)(gv.x >> 16))) * a[1];
;               float v2 = sigmoidf_(b2f((u16)(gv.y & 0xffff))) * a[2], v3 = sigmoidf_(b2f((u16)(gv.y >> 16))) * a[3];
;               uint2* mp = (uint2*)(g.outb + (size_t)tok * DM + n0);
;               if (g.epi != EPI_BR0) {
;                 const uint2 pv = *mp;
;                 v0 += b2f((u16)(pv.x & 0xffff)); v1 += b2f((u16)(pv.x >> 16));
;                 v2 += b2f((u16)(pv.y & 0xffff)); v3 += b2f((u16)(pv.y >> 16));
;               }
;               uint2 o; o.x = pack2(v0, v1); o.y = pack2(v2, v3);
;               *mp = o;
.Lmy_br_nopv_add_7_0:
	v_cvt_pk_bf16_f32 v236, v16, v17
	v_cvt_pk_bf16_f32 v237, v18, v19
	v_cvt_pk_bf16_f32 v238, v12, v13
	v_cvt_pk_bf16_f32 v239, v14, v15
	s_nop 1
	v_permlane16_swap_b32_e32 v236, v238
	v_permlane16_swap_b32_e32 v237, v239
	v_lshlrev_b32_e32 v228, 16, v216
	v_mul_f32_e32 v228, 0xbfb8aa3b, v228
	v_exp_f32_e32 v229, v228
	s_nop 0
	v_add_f32_e32 v229, 1.0, v229
	s_nop 0
	v_div_scale_f32 v230, s[2:3], v229, v229, 1.0
	v_rcp_f32_e32 v231, v230
	s_nop 0
	v_fma_f32 v232, -v230, v231, 1.0
	v_fmac_f32_e32 v231, v232, v231
	v_div_scale_f32 v233, vcc, 1.0, v229, 1.0
	v_mul_f32_e32 v234, v233, v231
	v_fma_f32 v235, -v230, v234, v233
	v_fmac_f32_e32 v234, v235, v231
	v_fma_f32 v230, -v230, v234, v233
	v_div_fmas_f32 v230, v230, v231, v234
	v_div_fixup_f32 v230, v230, v229, 1.0
	v_mul_f32_e32 v8, v8, v230
	v_and_b32_e32 v228, 0xffff0000, v216
	v_mul_f32_e32 v228, 0xbfb8aa3b, v228
	v_exp_f32_e32 v229, v228
	s_nop 0
	v_add_f32_e32 v229, 1.0, v229
	s_nop 0
	v_div_scale_f32 v230, s[2:3], v229, v229, 1.0
	v_rcp_f32_e32 v231, v230
	s_nop 0
	v_fma_f32 v232, -v230, v231, 1.0
	v_fmac_f32_e32 v231, v232, v231
	v_div_scale_f32 v233, vcc, 1.0, v229, 1.0
	v_mul_f32_e32 v234, v233, v231
	v_fma_f32 v235, -v230, v234, v233
	v_fmac_f32_e32 v234, v235, v231
	v_fma_f32 v230, -v230, v234, v233
	v_div_fmas_f32 v230, v230, v231, v234
	v_div_fixup_f32 v230, v230, v229, 1.0
	v_mul_f32_e32 v9, v9, v230
	v_lshlrev_b32_e32 v228, 16, v217
	v_mul_f32_e32 v228, 0xbfb8aa3b, v228
	v_exp_f32_e32 v229, v228
	s_nop 0
	v_add_f32_e32 v229, 1.0, v229
	s_nop 0
	v_div_scale_f32 v230, s[2:3], v229, v229, 1.0
	v_rcp_f32_e32 v231, v230
	s_nop 0
	v_fma_f32 v232, -v230, v231, 1.0
	v_fmac_f32_e32 v231, v232, v231
	v_div_scale_f32 v233, vcc, 1.0, v229, 1.0
	v_mul_f32_e32 v234, v233, v231
	v_fma_f32 v235, -v230, v234, v233
	v_fmac_f32_e32 v234, v235, v231
	v_fma_f32 v230, -v230, v234, v233
	v_div_fmas_f32 v230, v230, v231, v234
	v_div_fixup_f32 v230, v230, v229, 1.0
	v_mul_f32_e32 v10, v10, v230
	v_and_b32_e32 v228, 0xffff0000, v217
	v_mul_f32_e32 v228, 0xbfb8aa3b, v228
	v_exp_f32_e32 v229, v228
	s_nop 0
	v_add_f32_e32 v229, 1.0, v229
	s_nop 0
	v_div_scale_f32 v230, s[2:3], v229, v229, 1.0
	v_rcp_f32_e32 v231, v230
	s_nop 0
	v_fma_f32 v232, -v230, v231, 1.0
	v_fmac_f32_e32 v231, v232, v231
	v_div_scale_f32 v233, vcc, 1.0, v229, 1.0
	v_mul_f32_e32 v234, v233, v231
	v_fma_f32 v235, -v230, v234, v233
	v_fmac_f32_e32 v234, v235, v231
	v_fma_f32 v230, -v230, v234, v233
	v_div_fmas_f32 v230, v230, v231, v234
	v_div_fixup_f32 v230, v230, v229, 1.0
	v_mul_f32_e32 v11, v11, v230
	v_lshlrev_b32_e32 v228, 16, v218
	v_mul_f32_e32 v228, 0xbfb8aa3b, v228
	v_exp_f32_e32 v229, v228
	s_nop 0
	v_add_f32_e32 v229, 1.0, v229
	s_nop 0
	v_div_scale_f32 v230, s[2:3], v229, v229, 1.0
	v_rcp_f32_e32 v231, v230
	s_nop 0
	v_fma_f32 v232, -v230, v231, 1.0
	v_fmac_f32_e32 v231, v232, v231
	v_div_scale_f32 v233, vcc, 1.0, v229, 1.0
	v_mul_f32_e32 v234, v233, v231
	v_fma_f32 v235, -v230, v234, v233
	v_fmac_f32_e32 v234, v235, v231
	v_fma_f32 v230, -v230, v234, v233
	v_div_fmas_f32 v230, v230, v231, v234
	v_div_fixup_f32 v230, v230, v229, 1.0
	v_mul_f32_e32 v4, v4, v230
	v_and_b32_e32 v228, 0xffff0000, v218
	v_mul_f32_e32 v228, 0xbfb8aa3b, v228
	v_exp_f32_e32 v229, v228
	s_nop 0
	v_add_f32_e32 v229, 1.0, v229
	s_nop 0
	v_div_scale_f32 v230, s[2:3], v229, v229, 1.0
	v_rcp_f32_e32 v231, v230
	s_nop 0
	v_fma_f32 v232, -v230, v231, 1.0
	v_fmac_f32_e32 v231, v232, v231
	v_div_scale_f32 v233, vcc, 1.0, v229, 1.0
	v_mul_f32_e32 v234, v233, v231
	v_fma_f32 v235, -v230, v234, v233
	v_fmac_f32_e32 v234, v235, v231
	v_fma_f32 v230, -v230, v234, v233
	v_div_fmas_f32 v230, v230, v231, v234
	v_div_fixup_f32 v230, v230, v229, 1.0
	v_mul_f32_e32 v5, v5, v230
	v_lshlrev_b32_e32 v228, 16, v219
	v_mul_f32_e32 v228, 0xbfb8aa3b, v228
	v_exp_f32_e32 v229, v228
	s_nop 0
	v_add_f32_e32 v229, 1.0, v229
	s_nop 0
	v_div_scale_f32 v230, s[2:3], v229, v229, 1.0
	v_rcp_f32_e32 v231, v230
	s_nop 0
	v_fma_f32 v232, -v230, v231, 1.0
	v_fmac_f32_e32 v231, v232, v231
	v_div_scale_f32 v233, vcc, 1.0, v229, 1.0
	v_mul_f32_e32 v234, v233, v231
	v_fma_f32 v235, -v230, v234, v233
	v_fmac_f32_e32 v234, v235, v231
	v_fma_f32 v230, -v230, v234, v233
	v_div_fmas_f32 v230, v230, v231, v234
	v_div_fixup_f32 v230, v230, v229, 1.0
	v_mul_f32_e32 v6, v6, v230
	v_and_b32_e32 v228, 0xffff0000, v219
	v_mul_f32_e32 v228, 0xbfb8aa3b, v228
	v_exp_f32_e32 v229, v228
	s_nop 0
	v_add_f32_e32 v229, 1.0, v229
	s_nop 0
	v_div_scale_f32 v230, s[2:3], v229, v229, 1.0
	v_rcp_f32_e32 v231, v230
	s_nop 0
	v_fma_f32 v232, -v230, v231, 1.0
	v_fmac_f32_e32 v231, v232, v231
	v_div_scale_f32 v233, vcc, 1.0, v229, 1.0
	v_mul_f32_e32 v234, v233, v231
	v_fma_f32 v235, -v230, v234, v233
	v_fmac_f32_e32 v234, v235, v231
	v_fma_f32 v230, -v230, v234, v233
	v_div_fmas_f32 v230, v230, v231, v234
	v_div_fixup_f32 v230, v230, v229, 1.0
	v_mul_f32_e32 v7, v7, v230
	s_and_b64 vcc, exec, s[44:45]
	s_cbranch_vccz .Lmy_br_nopv_add_7_1
	v_lshlrev_b32_e32 v228, 16, v224
	v_add_f32_e32 v8, v8, v228
	v_and_b32_e32 v228, 0xffff0000, v224
	v_add_f32_e32 v9, v9, v228
	v_lshlrev_b32_e32 v228, 16, v225
	v_add_f32_e32 v10, v10, v228
	v_and_b32_e32 v228, 0xffff0000, v225
	v_add_f32_e32 v11, v11, v228
	v_lshlrev_b32_e32 v228, 16, v226
	v_add_f32_e32 v4, v4, v228
	v_and_b32_e32 v228, 0xffff0000, v226
	v_add_f32_e32 v5, v5, v228
	v_lshlrev_b32_e32 v228, 16, v227
	v_add_f32_e32 v6, v6, v228
	v_and_b32_e32 v228, 0xffff0000, v227
	v_add_f32_e32 v7, v7, v228
